# asymmetric priority: heavy 16-read loader segment keeps priority 1 (equal to its computing partner), light loader drops to 0
# baseline (speedup 1.0000x reference)
; #define PG8_STAGE(bufoff, gbase, voff) do { _Pragma("unroll") for (int _i = 0; _i < 2; ++_i) \
;         __builtin_amdgcn_global_load_lds((const unsigned*)((const char*)(gbase) + (voff)[_i]), (LAS unsigned*)(lds + (bufoff) + ldsw + _i * 8192), 16, 0, 0); } while (0)
; #define PG8_LDA(dst, b, h) do { _Pragma("unroll") for (int m = 0; m < 4; ++m) _Pragma("unroll") for (int k = 0; k < 2; ++k) dst[m][k] = *(const LAS bf16x8*)(lds + PG8_SA(b, h) + aoff + m * 2048 + k * 1024); } while (0)
; #define PG8_LDB(dst, b, h) do { _Pragma("unroll") for (int n = 0; n < 2; ++n) _Pragma("unroll") for (int k = 0; k < 2; ++k) dst[n][k] = *(const LAS bf16x8*)(lds + PG8_SB(b, h) + boff + n * 2048 + k * 1024); } while (0)
; #define PG8_MMA(ai, bj, At, Bt) do { __builtin_amdgcn_s_setprio(1); _Pragma("unroll") for (int m = 0; m < 4; ++m) _Pragma("unroll") for (int n = 0; n < 2; ++n) _Pragma("unroll") for (int k = 0; k < 2; ++k) \
;         acc[ai][bj][m][n] = __builtin_amdgcn_mfma_f32_16x16x32_bf16(Bt[n][k], At[m][k], acc[ai][bj][m][n], 0, 0, 0); __builtin_amdgcn_s_setprio(0); } while (0)
; #define PG8_WAIT_V(n) asm volatile("s_waitcnt vmcnt(" #n ")" ::: "memory")
; #define PG8_WAIT_L(n) asm volatile("s_waitcnt lgkmcnt(" #n ")" ::: "memory")
; #define PG8_BAR __builtin_amdgcn_s_barrier()
; #define PG8_SCHED __builtin_amdgcn_sched_barrier(0)
; template <class Epi, bool ALIGN_EPI, bool SP2 = PG8_SP2_DEFAULT>
; __device__ __forceinline__ void gemm_phase(LAS unsigned char* lds, const Gemm g, const StaticOrder& S, const Epi& E) {
;     ...
;             const bool last = (t == nt - 2);
;             const char* a1 = cA + (size_t)(t + 1) * kstep;
;             const char* a2 = last ? nA : cA + (size_t)(t + 2) * kstep; const char* b2 = last ? nB : cB + (size_t)(t + 2) * kstep;
;             const char* a3 = a2 + kstep; const char* b3 = b2 + kstep;
;             if constexpr (SP2) {
;             PG8_LDB(B0, 0, 0); PG8_LDB(B1, 0, 1); PG8_SCHED; PG8_LDA(At, 0, 0); PG8_STAGE(PG8_SA(1, 1), a1 + hstepA, voffA);
;             PG8_WAIT_V(8); PG8_WAIT_L(0); PG8_BAR; PG8_MMA(0, 0, At, B0); PG8_MMA(0, 1, At, B1); PG8_BAR; PG8_SCHED;
;             PG8_LDA(At, 0, 1); PG8_STAGE(PG8_SB(0, 0), b2, voffB); PG8_STAGE(PG8_SB(0, 1), b2 + hstepB, voffB); PG8_STAGE(PG8_SA(0, 0), a2, voffA);
;             PG8_WAIT_V(8); PG8_WAIT_L(0); PG8_BAR; PG8_MMA(1, 0, At, B0); PG8_MMA(1, 1, At, B1); PG8_BAR; PG8_SCHED;
.LBB0_250:
	ds_read_b128 v[150:153], v147
	ds_read_b128 v[154:157], v147 offset:1024
	ds_read_b128 v[158:161], v147 offset:2048
	ds_read_b128 v[162:165], v147 offset:3072
	ds_read_b128 v[166:169], v148
	ds_read_b128 v[170:173], v148 offset:1024
	ds_read_b128 v[174:177], v148 offset:2048
	ds_read_b128 v[178:181], v148 offset:3072
	s_add_u32 s20, s18, 0xfff00080
	s_addc_u32 s21, s19, -1
	s_cmp_eq_u32 s44, 60
	s_cselect_b32 s23, s13, s21
	s_cselect_b32 s22, s40, s20
	s_cselect_b32 s21, s11, s43
	s_cselect_b32 s20, s41, s42
	v_lshl_add_u64 v[206:207], s[18:19], 0, v[136:137]
	s_add_i32 m0, s9, 0xc000
	ds_read_b128 v[182:185], v149
	ds_read_b128 v[186:189], v149 offset:1024
	ds_read_b128 v[190:193], v149 offset:2048
	ds_read_b128 v[198:201], v149 offset:3072
	ds_read_b128 v[202:205], v149 offset:4096
	ds_read_b128 v[216:219], v149 offset:5120
	ds_read_b128 v[220:223], v149 offset:6144
	ds_read_b128 v[224:227], v149 offset:7168
	global_load_lds_dwordx4 v[206:207], off
	v_lshl_add_u64 v[206:207], s[18:19], 0, v[138:139]
	s_add_i32 m0, s9, 0xe000
	s_nop 0
	global_load_lds_dwordx4 v[206:207], off
	s_waitcnt vmcnt(8)
	s_waitcnt lgkmcnt(0)
	s_setprio 1
	s_barrier
	v_mfma_f32_16x16x32_bf16 v[124:127], v[150:153], v[182:185], v[124:127]
	v_mfma_f32_16x16x32_bf16 v[120:123], v[158:161], v[182:185], v[120:123]
	v_mfma_f32_16x16x32_bf16 v[116:119], v[150:153], v[190:193], v[116:119]
	v_mfma_f32_16x16x32_bf16 v[112:115], v[158:161], v[190:193], v[112:115]
	v_mfma_f32_16x16x32_bf16 v[100:103], v[150:153], v[202:205], v[100:103]
	v_mfma_f32_16x16x32_bf16 v[96:99], v[158:161], v[202:205], v[96:99]
	v_mfma_f32_16x16x32_bf16 v[84:87], v[150:153], v[220:223], v[84:87]
	v_mfma_f32_16x16x32_bf16 v[80:83], v[158:161], v[220:223], v[80:83]
	v_mfma_f32_16x16x32_bf16 v[124:127], v[154:157], v[186:189], v[124:127]
	v_mfma_f32_16x16x32_bf16 v[120:123], v[162:165], v[186:189], v[120:123]
	v_mfma_f32_16x16x32_bf16 v[116:119], v[154:157], v[198:201], v[116:119]
	v_mfma_f32_16x16x32_bf16 v[112:115], v[162:165], v[198:201], v[112:115]
	v_mfma_f32_16x16x32_bf16 v[100:103], v[154:157], v[216:219], v[100:103]
	v_mfma_f32_16x16x32_bf16 v[96:99], v[162:165], v[216:219], v[96:99]
	v_mfma_f32_16x16x32_bf16 v[84:87], v[154:157], v[224:227], v[84:87]
	v_mfma_f32_16x16x32_bf16 v[80:83], v[162:165], v[224:227], v[80:83]
	v_mfma_f32_16x16x32_bf16 v[108:111], v[166:169], v[182:185], v[108:111]
	v_mfma_f32_16x16x32_bf16 v[104:107], v[174:177], v[182:185], v[104:107]
	v_mfma_f32_16x16x32_bf16 v[92:95], v[166:169], v[190:193], v[92:95]
	v_mfma_f32_16x16x32_bf16 v[88:91], v[174:177], v[190:193], v[88:91]
	v_mfma_f32_16x16x32_bf16 v[76:79], v[166:169], v[202:205], v[76:79]
	v_mfma_f32_16x16x32_bf16 v[72:75], v[174:177], v[202:205], v[72:75]
	v_mfma_f32_16x16x32_bf16 v[68:71], v[166:169], v[220:223], v[68:71]
	v_mfma_f32_16x16x32_bf16 v[64:67], v[174:177], v[220:223], v[64:67]
	v_mfma_f32_16x16x32_bf16 v[108:111], v[170:173], v[186:189], v[108:111]
	v_mfma_f32_16x16x32_bf16 v[104:107], v[178:181], v[186:189], v[104:107]
	v_mfma_f32_16x16x32_bf16 v[92:95], v[170:173], v[198:201], v[92:95]
	v_mfma_f32_16x16x32_bf16 v[88:91], v[178:181], v[198:201], v[88:91]
	v_mfma_f32_16x16x32_bf16 v[76:79], v[170:173], v[216:219], v[76:79]
	v_mfma_f32_16x16x32_bf16 v[72:75], v[178:181], v[216:219], v[72:75]
	v_mfma_f32_16x16x32_bf16 v[68:71], v[170:173], v[224:227], v[68:71]
	v_mfma_f32_16x16x32_bf16 v[64:67], v[178:181], v[224:227], v[64:67]
	s_barrier
	s_setprio 0
	s_add_i32 s45, s36, s24
	v_lshl_add_u64 v[206:207], s[20:21], 0, v[132:133]
	s_mov_b32 m0, s45
	ds_read_b128 v[182:185], v149 offset:16384
	ds_read_b128 v[186:189], v149 offset:17408
	ds_read_b128 v[190:193], v149 offset:18432
	ds_read_b128 v[198:201], v149 offset:19456
	ds_read_b128 v[202:205], v149 offset:20480
	ds_read_b128 v[216:219], v149 offset:21504
	ds_read_b128 v[220:223], v149 offset:22528
	ds_read_b128 v[224:227], v149 offset:23552
	global_load_lds_dwordx4 v[206:207], off
	s_add_i32 m0, s45, 0x2000
	s_add_u32 s46, s20, 0x100000
	v_lshl_add_u64 v[210:211], s[20:21], 0, v[128:129]
	s_addc_u32 s47, s21, 0
	s_add_i32 s45, s37, s24
	global_load_lds_dwordx4 v[210:211], off
	v_lshl_add_u64 v[228:229], s[46:47], 0, v[132:133]
	s_mov_b32 m0, s45
	v_lshl_add_u64 v[230:231], s[22:23], 0, v[130:131]
	global_load_lds_dwordx4 v[228:229], off
	v_lshl_add_u64 v[228:229], s[46:47], 0, v[128:129]
	s_add_i32 m0, s45, 0x2000
	s_nop 0
	global_load_lds_dwordx4 v[228:229], off
	v_lshl_add_u64 v[228:229], s[22:23], 0, v[134:135]
	s_mov_b32 m0, s9
	s_nop 0
	global_load_lds_dwordx4 v[228:229], off
	s_mov_b32 m0, s27
	s_nop 0
	global_load_lds_dwordx4 v[230:231], off
	s_waitcnt vmcnt(8)
	s_waitcnt lgkmcnt(0)
	s_setprio 1
	s_barrier
; #define PG8_STAGE(bufoff, gbase, voff) do { _Pragma("unroll") for (int _i = 0; _i < 2; ++_i) \
;         __builtin_amdgcn_global_load_lds((const unsigned*)((const char*)(gbase) + (voff)[_i]), (LAS unsigned*)(lds + (bufoff) + ldsw + _i * 8192), 16, 0, 0); } while (0)
; #define PG8_LDA(dst, b, h) do { _Pragma("unroll") for (int m = 0; m < 4; ++m) _Pragma("unroll") for (int k = 0; k < 2; ++k) dst[m][k] = *(const LAS bf16x8*)(lds + PG8_SA(b, h) + aoff + m * 2048 + k * 1024); } while (0)
; #define PG8_LDB(dst, b, h) do { _Pragma("unroll") for (int n = 0; n < 2; ++n) _Pragma("unroll") for (int k = 0; k < 2; ++k) dst[n][k] = *(const LAS bf16x8*)(lds + PG8_SB(b, h) + boff + n * 2048 + k * 1024); } while (0)
; #define PG8_MMA(ai, bj, At, Bt) do { __builtin_amdgcn_s_setprio(1); _Pragma("unroll") for (int m = 0; m < 4; ++m) _Pragma("unroll") for (int n = 0; n < 2; ++n) _Pragma("unroll") for (int k = 0; k < 2; ++k) \
;         acc[ai][bj][m][n] = __builtin_amdgcn_mfma_f32_16x16x32_bf16(Bt[n][k], At[m][k], acc[ai][bj][m][n], 0, 0, 0); __builtin_amdgcn_s_setprio(0); } while (0)
; #define PG8_WAIT_V(n) asm volatile("s_waitcnt vmcnt(" #n ")" ::: "memory")
; #define PG8_WAIT_L(n) asm volatile("s_waitcnt lgkmcnt(" #n ")" ::: "memory")
; #define PG8_BAR __builtin_amdgcn_s_barrier()
; #define PG8_SCHED __builtin_amdgcn_sched_barrier(0)
; template <class Epi, bool ALIGN_EPI, bool SP2 = PG8_SP2_DEFAULT>
; __device__ __forceinline__ void gemm_phase(LAS unsigned char* lds, const Gemm g, const StaticOrder& S, const Epi& E) {
;     ...
;             PG8_WAIT_V(8); PG8_WAIT_L(0); PG8_BAR; PG8_MMA(1, 0, At, B0); PG8_MMA(1, 1, At, B1); PG8_BAR; PG8_SCHED;
;             PG8_LDB(B0, 1, 0); PG8_LDB(B1, 1, 1); PG8_SCHED; PG8_LDA(At, 1, 0); PG8_STAGE(PG8_SA(0, 1), a2 + hstepA, voffA);
;             PG8_WAIT_V(8); PG8_WAIT_L(0); PG8_BAR; PG8_MMA(0, 0, At, B0); PG8_MMA(0, 1, At, B1); PG8_BAR; PG8_SCHED;
	v_mfma_f32_16x16x32_bf16 v[60:63], v[150:153], v[182:185], v[60:63]
	v_mfma_f32_16x16x32_bf16 v[56:59], v[158:161], v[182:185], v[56:59]
	v_mfma_f32_16x16x32_bf16 v[52:55], v[150:153], v[190:193], v[52:55]
	v_mfma_f32_16x16x32_bf16 v[48:51], v[158:161], v[190:193], v[48:51]
	v_mfma_f32_16x16x32_bf16 v[36:39], v[150:153], v[202:205], v[36:39]
	v_mfma_f32_16x16x32_bf16 v[32:35], v[158:161], v[202:205], v[32:35]
	v_mfma_f32_16x16x32_bf16 v[20:23], v[150:153], v[220:223], v[20:23]
	v_mfma_f32_16x16x32_bf16 v[16:19], v[158:161], v[220:223], v[16:19]
	v_mfma_f32_16x16x32_bf16 v[60:63], v[154:157], v[186:189], v[60:63]
	v_mfma_f32_16x16x32_bf16 v[56:59], v[162:165], v[186:189], v[56:59]
	v_mfma_f32_16x16x32_bf16 v[52:55], v[154:157], v[198:201], v[52:55]
	v_mfma_f32_16x16x32_bf16 v[48:51], v[162:165], v[198:201], v[48:51]
	v_mfma_f32_16x16x32_bf16 v[36:39], v[154:157], v[216:219], v[36:39]
	v_mfma_f32_16x16x32_bf16 v[32:35], v[162:165], v[216:219], v[32:35]
	v_mfma_f32_16x16x32_bf16 v[20:23], v[154:157], v[224:227], v[20:23]
	v_mfma_f32_16x16x32_bf16 v[16:19], v[162:165], v[224:227], v[16:19]
	v_mfma_f32_16x16x32_bf16 v[44:47], v[166:169], v[182:185], v[44:47]
	v_mfma_f32_16x16x32_bf16 v[40:43], v[174:177], v[182:185], v[40:43]
	v_mfma_f32_16x16x32_bf16 v[28:31], v[166:169], v[190:193], v[28:31]
	v_mfma_f32_16x16x32_bf16 v[24:27], v[174:177], v[190:193], v[24:27]
	v_mfma_f32_16x16x32_bf16 v[12:15], v[166:169], v[202:205], v[12:15]
	v_mfma_f32_16x16x32_bf16 v[8:11], v[174:177], v[202:205], v[8:11]
	v_mfma_f32_16x16x32_bf16 v[4:7], v[166:169], v[220:223], v[4:7]
	v_mfma_f32_16x16x32_bf16 v[0:3], v[174:177], v[220:223], v[0:3]
	v_mfma_f32_16x16x32_bf16 v[44:47], v[170:173], v[186:189], v[44:47]
	v_mfma_f32_16x16x32_bf16 v[40:43], v[178:181], v[186:189], v[40:43]
	v_mfma_f32_16x16x32_bf16 v[28:31], v[170:173], v[198:201], v[28:31]
	v_mfma_f32_16x16x32_bf16 v[24:27], v[178:181], v[198:201], v[24:27]
	v_mfma_f32_16x16x32_bf16 v[12:15], v[170:173], v[216:219], v[12:15]
	v_mfma_f32_16x16x32_bf16 v[8:11], v[178:181], v[216:219], v[8:11]
	v_mfma_f32_16x16x32_bf16 v[4:7], v[170:173], v[224:227], v[4:7]
	v_mfma_f32_16x16x32_bf16 v[0:3], v[178:181], v[224:227], v[0:3]
	s_barrier
	s_add_i32 s45, 0, 0x18000
	s_add_i32 s46, 0, 0x1c000
	v_add_u32_e32 v162, s45, v145
	v_add_u32_e32 v178, s46, v145
	ds_read_b128 v[150:153], v162
	ds_read_b128 v[154:157], v162 offset:1024
	ds_read_b128 v[158:161], v162 offset:2048
	ds_read_b128 v[162:165], v162 offset:3072
	ds_read_b128 v[166:169], v178
	ds_read_b128 v[170:173], v178 offset:1024
	ds_read_b128 v[174:177], v178 offset:2048
	ds_read_b128 v[178:181], v178 offset:3072
	s_add_u32 s22, s22, 0x100000
	s_addc_u32 s23, s23, 0
	s_mov_b32 m0, s28
	v_lshl_add_u64 v[232:233], s[22:23], 0, v[134:135]
	ds_read_b128 v[182:185], v149 offset:32768
	ds_read_b128 v[186:189], v149 offset:33792
	ds_read_b128 v[190:193], v149 offset:34816
	ds_read_b128 v[198:201], v149 offset:35840
	ds_read_b128 v[202:205], v149 offset:36864
	ds_read_b128 v[216:219], v149 offset:37888
	ds_read_b128 v[220:223], v149 offset:38912
	ds_read_b128 v[224:227], v149 offset:39936
	global_load_lds_dwordx4 v[232:233], off
	v_lshl_add_u64 v[232:233], s[22:23], 0, v[130:131]
	s_mov_b32 m0, s29
	s_nop 0
	global_load_lds_dwordx4 v[232:233], off
	s_waitcnt vmcnt(8)
	s_waitcnt lgkmcnt(0)
	s_setprio 1
	s_barrier
	v_mfma_f32_16x16x32_bf16 v[124:127], v[150:153], v[182:185], v[124:127]
	v_mfma_f32_16x16x32_bf16 v[120:123], v[158:161], v[182:185], v[120:123]
	v_mfma_f32_16x16x32_bf16 v[116:119], v[150:153], v[190:193], v[116:119]
	v_mfma_f32_16x16x32_bf16 v[112:115], v[158:161], v[190:193], v[112:115]
	v_mfma_f32_16x16x32_bf16 v[100:103], v[150:153], v[202:205], v[100:103]
	v_mfma_f32_16x16x32_bf16 v[96:99], v[158:161], v[202:205], v[96:99]
	v_mfma_f32_16x16x32_bf16 v[84:87], v[150:153], v[220:223], v[84:87]
	v_mfma_f32_16x16x32_bf16 v[80:83], v[158:161], v[220:223], v[80:83]
	v_mfma_f32_16x16x32_bf16 v[124:127], v[154:157], v[186:189], v[124:127]
	v_mfma_f32_16x16x32_bf16 v[120:123], v[162:165], v[186:189], v[120:123]
	v_mfma_f32_16x16x32_bf16 v[116:119], v[154:157], v[198:201], v[116:119]
	v_mfma_f32_16x16x32_bf16 v[112:115], v[162:165], v[198:201], v[112:115]
	v_mfma_f32_16x16x32_bf16 v[100:103], v[154:157], v[216:219], v[100:103]
	v_mfma_f32_16x16x32_bf16 v[96:99], v[162:165], v[216:219], v[96:99]
	v_mfma_f32_16x16x32_bf16 v[84:87], v[154:157], v[224:227], v[84:87]
	v_mfma_f32_16x16x32_bf16 v[80:83], v[162:165], v[224:227], v[80:83]
	v_mfma_f32_16x16x32_bf16 v[108:111], v[166:169], v[182:185], v[108:111]
	v_mfma_f32_16x16x32_bf16 v[104:107], v[174:177], v[182:185], v[104:107]
	v_mfma_f32_16x16x32_bf16 v[92:95], v[166:169], v[190:193], v[92:95]
	v_mfma_f32_16x16x32_bf16 v[88:91], v[174:177], v[190:193], v[88:91]
	v_mfma_f32_16x16x32_bf16 v[76:79], v[166:169], v[202:205], v[76:79]
	v_mfma_f32_16x16x32_bf16 v[72:75], v[174:177], v[202:205], v[72:75]
	v_mfma_f32_16x16x32_bf16 v[68:71], v[166:169], v[220:223], v[68:71]
	v_mfma_f32_16x16x32_bf16 v[64:67], v[174:177], v[220:223], v[64:67]
	v_mfma_f32_16x16x32_bf16 v[108:111], v[170:173], v[186:189], v[108:111]
	v_mfma_f32_16x16x32_bf16 v[104:107], v[178:181], v[186:189], v[104:107]
	v_mfma_f32_16x16x32_bf16 v[92:95], v[170:173], v[198:201], v[92:95]
	v_mfma_f32_16x16x32_bf16 v[88:91], v[178:181], v[198:201], v[88:91]
	v_mfma_f32_16x16x32_bf16 v[76:79], v[170:173], v[216:219], v[76:79]
	v_mfma_f32_16x16x32_bf16 v[72:75], v[178:181], v[216:219], v[72:75]
	v_mfma_f32_16x16x32_bf16 v[68:71], v[170:173], v[224:227], v[68:71]
	v_mfma_f32_16x16x32_bf16 v[64:67], v[178:181], v[224:227], v[64:67]
	s_barrier
; #define PG8_STAGE(bufoff, gbase, voff) do { _Pragma("unroll") for (int _i = 0; _i < 2; ++_i) \
;         __builtin_amdgcn_global_load_lds((const unsigned*)((const char*)(gbase) + (voff)[_i]), (LAS unsigned*)(lds + (bufoff) + ldsw + _i * 8192), 16, 0, 0); } while (0)
; #define PG8_LDA(dst, b, h) do { _Pragma("unroll") for (int m = 0; m < 4; ++m) _Pragma("unroll") for (int k = 0; k < 2; ++k) dst[m][k] = *(const LAS bf16x8*)(lds + PG8_SA(b, h) + aoff + m * 2048 + k * 1024); } while (0)
; #define PG8_MMA(ai, bj, At, Bt) do { __builtin_amdgcn_s_setprio(1); _Pragma("unroll") for (int m = 0; m < 4; ++m) _Pragma("unroll") for (int n = 0; n < 2; ++n) _Pragma("unroll") for (int k = 0; k < 2; ++k) \
;         acc[ai][bj][m][n] = __builtin_amdgcn_mfma_f32_16x16x32_bf16(Bt[n][k], At[m][k], acc[ai][bj][m][n], 0, 0, 0); __builtin_amdgcn_s_setprio(0); } while (0)
; #define PG8_WAIT_V(n) asm volatile("s_waitcnt vmcnt(" #n ")" ::: "memory")
; #define PG8_WAIT_L(n) asm volatile("s_waitcnt lgkmcnt(" #n ")" ::: "memory")
; #define PG8_BAR __builtin_amdgcn_s_barrier()
; #define PG8_SCHED __builtin_amdgcn_sched_barrier(0)
; template <class Epi, bool ALIGN_EPI, bool SP2 = PG8_SP2_DEFAULT>
; __device__ __forceinline__ void gemm_phase(LAS unsigned char* lds, const Gemm g, const StaticOrder& S, const Epi& E) {
;     ...
;         for (int t = 0; t < nt; t += 2) {
;             const bool last = (t == nt - 2);
;     ...
;             PG8_LDA(At, 1, 1); PG8_STAGE(PG8_SB(1, 0), b3, voffB); PG8_STAGE(PG8_SB(1, 1), b3 + hstepB, voffB); PG8_STAGE(PG8_SA(1, 0), a3, voffA);
;             PG8_WAIT_V(8); PG8_WAIT_L(0); PG8_BAR; PG8_MMA(1, 0, At, B0); PG8_MMA(1, 1, At, B1); PG8_BAR; PG8_SCHED;
	s_setprio 0
	s_add_i32 s22, s45, s24
	v_lshl_add_u64 v[206:207], v[206:207], 0, s[4:5]
	s_mov_b32 m0, s22
	ds_read_b128 v[182:185], v149 offset:49152
	ds_read_b128 v[186:189], v149 offset:50176
	ds_read_b128 v[190:193], v149 offset:51200
	ds_read_b128 v[198:201], v149 offset:52224
	ds_read_b128 v[202:205], v149 offset:53248
	ds_read_b128 v[216:219], v149 offset:54272
	ds_read_b128 v[220:223], v149 offset:55296
	ds_read_b128 v[224:227], v149 offset:56320
	global_load_lds_dwordx4 v[206:207], off
	s_add_i32 m0, s22, 0x2000
	s_add_u32 s20, s20, 0x100080
	v_lshl_add_u64 v[206:207], v[210:211], 0, s[4:5]
	s_addc_u32 s21, s21, 0
	s_add_i32 s22, s46, s24
	global_load_lds_dwordx4 v[206:207], off
	v_lshl_add_u64 v[206:207], s[20:21], 0, v[132:133]
	s_mov_b32 m0, s22
	s_nop 0
	global_load_lds_dwordx4 v[206:207], off
	v_lshl_add_u64 v[206:207], s[20:21], 0, v[128:129]
	s_add_i32 m0, s22, 0x2000
	s_nop 0
	global_load_lds_dwordx4 v[206:207], off
	v_lshl_add_u64 v[206:207], v[228:229], 0, s[4:5]
	s_mov_b32 m0, s33
	s_nop 0
	global_load_lds_dwordx4 v[206:207], off
	v_lshl_add_u64 v[206:207], v[230:231], 0, s[4:5]
	s_mov_b32 m0, s34
	s_nop 0
	global_load_lds_dwordx4 v[206:207], off
	s_waitcnt vmcnt(8)
	s_waitcnt lgkmcnt(0)
	s_setprio 1
	s_barrier
	v_mfma_f32_16x16x32_bf16 v[60:63], v[150:153], v[182:185], v[60:63]
	v_mfma_f32_16x16x32_bf16 v[56:59], v[158:161], v[182:185], v[56:59]
	v_mfma_f32_16x16x32_bf16 v[52:55], v[150:153], v[190:193], v[52:55]
	v_mfma_f32_16x16x32_bf16 v[48:51], v[158:161], v[190:193], v[48:51]
	v_mfma_f32_16x16x32_bf16 v[36:39], v[150:153], v[202:205], v[36:39]
	v_mfma_f32_16x16x32_bf16 v[32:35], v[158:161], v[202:205], v[32:35]
	v_mfma_f32_16x16x32_bf16 v[20:23], v[150:153], v[220:223], v[20:23]
	v_mfma_f32_16x16x32_bf16 v[16:19], v[158:161], v[220:223], v[16:19]
	v_mfma_f32_16x16x32_bf16 v[60:63], v[154:157], v[186:189], v[60:63]
	v_mfma_f32_16x16x32_bf16 v[56:59], v[162:165], v[186:189], v[56:59]
	v_mfma_f32_16x16x32_bf16 v[52:55], v[154:157], v[198:201], v[52:55]
	v_mfma_f32_16x16x32_bf16 v[48:51], v[162:165], v[198:201], v[48:51]
	v_mfma_f32_16x16x32_bf16 v[36:39], v[154:157], v[216:219], v[36:39]
	v_mfma_f32_16x16x32_bf16 v[32:35], v[162:165], v[216:219], v[32:35]
	v_mfma_f32_16x16x32_bf16 v[20:23], v[154:157], v[224:227], v[20:23]
	v_mfma_f32_16x16x32_bf16 v[16:19], v[162:165], v[224:227], v[16:19]
	v_mfma_f32_16x16x32_bf16 v[44:47], v[166:169], v[182:185], v[44:47]
	v_mfma_f32_16x16x32_bf16 v[40:43], v[174:177], v[182:185], v[40:43]
	v_mfma_f32_16x16x32_bf16 v[28:31], v[166:169], v[190:193], v[28:31]
	v_mfma_f32_16x16x32_bf16 v[24:27], v[174:177], v[190:193], v[24:27]
	v_mfma_f32_16x16x32_bf16 v[12:15], v[166:169], v[202:205], v[12:15]
	v_mfma_f32_16x16x32_bf16 v[8:11], v[174:177], v[202:205], v[8:11]
	v_mfma_f32_16x16x32_bf16 v[4:7], v[166:169], v[220:223], v[4:7]
	v_mfma_f32_16x16x32_bf16 v[0:3], v[174:177], v[220:223], v[0:3]
	v_mfma_f32_16x16x32_bf16 v[44:47], v[170:173], v[186:189], v[44:47]
	v_mfma_f32_16x16x32_bf16 v[40:43], v[178:181], v[186:189], v[40:43]
	v_mfma_f32_16x16x32_bf16 v[28:31], v[170:173], v[198:201], v[28:31]
	v_mfma_f32_16x16x32_bf16 v[24:27], v[178:181], v[198:201], v[24:27]
	v_mfma_f32_16x16x32_bf16 v[12:15], v[170:173], v[216:219], v[12:15]
	v_mfma_f32_16x16x32_bf16 v[8:11], v[178:181], v[216:219], v[8:11]
	v_mfma_f32_16x16x32_bf16 v[4:7], v[170:173], v[224:227], v[4:7]
	v_mfma_f32_16x16x32_bf16 v[0:3], v[178:181], v[224:227], v[0:3]
	s_barrier
	s_add_i32 s44, s44, 2
	s_add_u32 s18, s18, 0x100
	s_addc_u32 s19, s19, 0
	s_add_u32 s42, s42, 0x100
	s_addc_u32 s43, s43, 0
	s_cmp_gt_u32 s44, 61
	s_cbranch_scc0 .LBB0_250
	s_and_b64 vcc, exec, s[6:7]
	s_cbranch_vccz .LBB0_253
	s_barrier

; #define PG8_STAGE(bufoff, gbase, voff) do { _Pragma("unroll") for (int _i = 0; _i < 2; ++_i) \
;         __builtin_amdgcn_global_load_lds((const unsigned*)((const char*)(gbase) + (voff)[_i]), (LAS unsigned*)(lds + (bufoff) + ldsw + _i * 8192), 16, 0, 0); } while (0)
; #define PG8_LDA(dst, b, h) do { _Pragma("unroll") for (int m = 0; m < 4; ++m) _Pragma("unroll") for (int k = 0; k < 2; ++k) dst[m][k] = *(const LAS bf16x8*)(lds + PG8_SA(b, h) + aoff + m * 2048 + k * 1024); } while (0)
; #define PG8_LDB(dst, b, h) do { _Pragma("unroll") for (int n = 0; n < 2; ++n) _Pragma("unroll") for (int k = 0; k < 2; ++k) dst[n][k] = *(const LAS bf16x8*)(lds + PG8_SB(b, h) + boff + n * 2048 + k * 1024); } while (0)
; #define PG8_MMA(ai, bj, At, Bt) do { __builtin_amdgcn_s_setprio(1); _Pragma("unroll") for (int m = 0; m < 4; ++m) _Pragma("unroll") for (int n = 0; n < 2; ++n) _Pragma("unroll") for (int k = 0; k < 2; ++k) \
;         acc[ai][bj][m][n] = __builtin_amdgcn_mfma_f32_16x16x32_bf16(Bt[n][k], At[m][k], acc[ai][bj][m][n], 0, 0, 0); __builtin_amdgcn_s_setprio(0); } while (0)
; #define PG8_WAIT_V(n) asm volatile("s_waitcnt vmcnt(" #n ")" ::: "memory")
; #define PG8_WAIT_L(n) asm volatile("s_waitcnt lgkmcnt(" #n ")" ::: "memory")
; #define PG8_BAR __builtin_amdgcn_s_barrier()
; #define PG8_SCHED __builtin_amdgcn_sched_barrier(0)
; template <class Epi, bool ALIGN_EPI, bool SP2 = PG8_SP2_DEFAULT>
; __device__ __forceinline__ void gemm_phase(LAS unsigned char* lds, const Gemm g, const StaticOrder& S, const Epi& E) {
;     ...
;             const bool last = (t == nt - 2);
;             const char* a1 = cA + (size_t)(t + 1) * kstep;
;             const char* a2 = last ? nA : cA + (size_t)(t + 2) * kstep; const char* b2 = last ? nB : cB + (size_t)(t + 2) * kstep;
;             const char* a3 = a2 + kstep; const char* b3 = b2 + kstep;
;             if constexpr (SP2) {
;             PG8_LDB(B0, 0, 0); PG8_LDB(B1, 0, 1); PG8_SCHED; PG8_LDA(At, 0, 0); PG8_STAGE(PG8_SA(1, 1), a1 + hstepA, voffA);
;             PG8_WAIT_V(8); PG8_WAIT_L(0); PG8_BAR; PG8_MMA(0, 0, At, B0); PG8_MMA(0, 1, At, B1); PG8_BAR; PG8_SCHED;
;             PG8_LDA(At, 0, 1); PG8_STAGE(PG8_SB(0, 0), b2, voffB); PG8_STAGE(PG8_SB(0, 1), b2 + hstepB, voffB); PG8_STAGE(PG8_SA(0, 0), a2, voffA);
;             PG8_WAIT_V(8); PG8_WAIT_L(0); PG8_BAR; PG8_MMA(1, 0, At, B0); PG8_MMA(1, 1, At, B1); PG8_BAR; PG8_SCHED;
.LBB0_428:
	ds_read_b128 v[128:131], v165
	ds_read_b128 v[132:135], v165 offset:1024
	ds_read_b128 v[136:139], v165 offset:2048
	ds_read_b128 v[140:143], v165 offset:3072
	ds_read_b128 v[168:171], v166
	ds_read_b128 v[172:175], v166 offset:1024
	ds_read_b128 v[176:179], v166 offset:2048
	ds_read_b128 v[180:183], v166 offset:3072
	s_add_u32 s24, s22, 0xfffe0080
	s_addc_u32 s25, s23, -1
	s_cmp_eq_u32 s51, 4
	s_cselect_b32 s27, s15, s25
	s_cselect_b32 s26, s47, s24
	s_cselect_b32 s25, s13, s50
	s_cselect_b32 s24, s48, s49
	v_lshl_add_u64 v[160:161], s[22:23], 0, v[152:153]
	s_add_i32 m0, s21, 0xc000
	ds_read_b128 v[184:187], v167
	ds_read_b128 v[188:191], v167 offset:1024
	ds_read_b128 v[198:201], v167 offset:2048
	ds_read_b128 v[202:205], v167 offset:3072
	ds_read_b128 v[216:219], v167 offset:4096
	ds_read_b128 v[220:223], v167 offset:5120
	ds_read_b128 v[224:227], v167 offset:6144
	ds_read_b128 v[228:231], v167 offset:7168
	global_load_lds_dwordx4 v[160:161], off
	v_lshl_add_u64 v[160:161], s[22:23], 0, v[154:155]
	s_add_i32 m0, s21, 0xe000
	s_nop 0
	global_load_lds_dwordx4 v[160:161], off
	s_waitcnt vmcnt(8)
	s_waitcnt lgkmcnt(0)
	s_setprio 1
	s_barrier
	v_mfma_f32_16x16x32_bf16 v[124:127], v[128:131], v[184:187], v[124:127]
	v_mfma_f32_16x16x32_bf16 v[120:123], v[136:139], v[184:187], v[120:123]
	v_mfma_f32_16x16x32_bf16 v[116:119], v[128:131], v[198:201], v[116:119]
	v_mfma_f32_16x16x32_bf16 v[112:115], v[136:139], v[198:201], v[112:115]
	v_mfma_f32_16x16x32_bf16 v[108:111], v[128:131], v[216:219], v[108:111]
	v_mfma_f32_16x16x32_bf16 v[100:103], v[136:139], v[216:219], v[100:103]
	v_mfma_f32_16x16x32_bf16 v[80:83], v[128:131], v[224:227], v[80:83]
	v_mfma_f32_16x16x32_bf16 v[72:75], v[136:139], v[224:227], v[72:75]
	v_mfma_f32_16x16x32_bf16 v[124:127], v[132:135], v[188:191], v[124:127]
	v_mfma_f32_16x16x32_bf16 v[120:123], v[140:143], v[188:191], v[120:123]
	v_mfma_f32_16x16x32_bf16 v[116:119], v[132:135], v[202:205], v[116:119]
	v_mfma_f32_16x16x32_bf16 v[112:115], v[140:143], v[202:205], v[112:115]
	v_mfma_f32_16x16x32_bf16 v[108:111], v[132:135], v[220:223], v[108:111]
	v_mfma_f32_16x16x32_bf16 v[100:103], v[140:143], v[220:223], v[100:103]
	v_mfma_f32_16x16x32_bf16 v[80:83], v[132:135], v[228:231], v[80:83]
	v_mfma_f32_16x16x32_bf16 v[72:75], v[140:143], v[228:231], v[72:75]
	v_mfma_f32_16x16x32_bf16 v[104:107], v[168:171], v[184:187], v[104:107]
	v_mfma_f32_16x16x32_bf16 v[96:99], v[176:179], v[184:187], v[96:99]
	v_mfma_f32_16x16x32_bf16 v[92:95], v[168:171], v[198:201], v[92:95]
	v_mfma_f32_16x16x32_bf16 v[88:91], v[176:179], v[198:201], v[88:91]
	v_mfma_f32_16x16x32_bf16 v[84:87], v[168:171], v[216:219], v[84:87]
	v_mfma_f32_16x16x32_bf16 v[76:79], v[176:179], v[216:219], v[76:79]
	v_mfma_f32_16x16x32_bf16 v[68:71], v[168:171], v[224:227], v[68:71]
	v_mfma_f32_16x16x32_bf16 v[64:67], v[176:179], v[224:227], v[64:67]
	v_mfma_f32_16x16x32_bf16 v[104:107], v[172:175], v[188:191], v[104:107]
	v_mfma_f32_16x16x32_bf16 v[96:99], v[180:183], v[188:191], v[96:99]
	v_mfma_f32_16x16x32_bf16 v[92:95], v[172:175], v[202:205], v[92:95]
	v_mfma_f32_16x16x32_bf16 v[88:91], v[180:183], v[202:205], v[88:91]
	v_mfma_f32_16x16x32_bf16 v[84:87], v[172:175], v[220:223], v[84:87]
	v_mfma_f32_16x16x32_bf16 v[76:79], v[180:183], v[220:223], v[76:79]
	v_mfma_f32_16x16x32_bf16 v[68:71], v[172:175], v[228:231], v[68:71]
	v_mfma_f32_16x16x32_bf16 v[64:67], v[180:183], v[228:231], v[64:67]
	s_barrier
	s_setprio 0
	s_add_i32 s52, s40, s29
	v_lshl_add_u64 v[160:161], s[24:25], 0, v[146:147]
	s_mov_b32 m0, s52
	ds_read_b128 v[184:187], v167 offset:16384
	ds_read_b128 v[188:191], v167 offset:17408
	ds_read_b128 v[198:201], v167 offset:18432
	ds_read_b128 v[202:205], v167 offset:19456
	ds_read_b128 v[216:219], v167 offset:20480
	ds_read_b128 v[220:223], v167 offset:21504
	ds_read_b128 v[224:227], v167 offset:22528
	ds_read_b128 v[228:231], v167 offset:23552
	global_load_lds_dwordx4 v[160:161], off
	s_add_i32 m0, s52, 0x2000
	s_add_u32 s52, s24, 0x20000
	v_lshl_add_u64 v[192:193], s[24:25], 0, v[150:151]
	s_addc_u32 s53, s25, 0
	s_add_i32 s54, s41, s29
	global_load_lds_dwordx4 v[192:193], off
	v_lshl_add_u64 v[206:207], s[52:53], 0, v[146:147]
	s_mov_b32 m0, s54
	v_lshl_add_u64 v[210:211], s[26:27], 0, v[148:149]
	global_load_lds_dwordx4 v[206:207], off
	v_lshl_add_u64 v[206:207], s[52:53], 0, v[150:151]
	s_add_i32 m0, s54, 0x2000
	s_nop 0
	global_load_lds_dwordx4 v[206:207], off
	v_lshl_add_u64 v[206:207], s[26:27], 0, v[144:145]
	s_mov_b32 m0, s21
	s_nop 0
	global_load_lds_dwordx4 v[206:207], off
	s_mov_b32 m0, s30
	s_nop 0
	global_load_lds_dwordx4 v[210:211], off
	s_waitcnt vmcnt(8)
	s_waitcnt lgkmcnt(0)
	s_setprio 1
	s_barrier
; #define PG8_STAGE(bufoff, gbase, voff) do { _Pragma("unroll") for (int _i = 0; _i < 2; ++_i) \
;         __builtin_amdgcn_global_load_lds((const unsigned*)((const char*)(gbase) + (voff)[_i]), (LAS unsigned*)(lds + (bufoff) + ldsw + _i * 8192), 16, 0, 0); } while (0)
; #define PG8_LDA(dst, b, h) do { _Pragma("unroll") for (int m = 0; m < 4; ++m) _Pragma("unroll") for (int k = 0; k < 2; ++k) dst[m][k] = *(const LAS bf16x8*)(lds + PG8_SA(b, h) + aoff + m * 2048 + k * 1024); } while (0)
; #define PG8_LDB(dst, b, h) do { _Pragma("unroll") for (int n = 0; n < 2; ++n) _Pragma("unroll") for (int k = 0; k < 2; ++k) dst[n][k] = *(const LAS bf16x8*)(lds + PG8_SB(b, h) + boff + n * 2048 + k * 1024); } while (0)
; #define PG8_MMA(ai, bj, At, Bt) do { __builtin_amdgcn_s_setprio(1); _Pragma("unroll") for (int m = 0; m < 4; ++m) _Pragma("unroll") for (int n = 0; n < 2; ++n) _Pragma("unroll") for (int k = 0; k < 2; ++k) \
;         acc[ai][bj][m][n] = __builtin_amdgcn_mfma_f32_16x16x32_bf16(Bt[n][k], At[m][k], acc[ai][bj][m][n], 0, 0, 0); __builtin_amdgcn_s_setprio(0); } while (0)
; #define PG8_WAIT_V(n) asm volatile("s_waitcnt vmcnt(" #n ")" ::: "memory")
; #define PG8_WAIT_L(n) asm volatile("s_waitcnt lgkmcnt(" #n ")" ::: "memory")
; #define PG8_BAR __builtin_amdgcn_s_barrier()
; #define PG8_SCHED __builtin_amdgcn_sched_barrier(0)
; template <class Epi, bool ALIGN_EPI, bool SP2 = PG8_SP2_DEFAULT>
; __device__ __forceinline__ void gemm_phase(LAS unsigned char* lds, const Gemm g, const StaticOrder& S, const Epi& E) {
;     ...
;             PG8_WAIT_V(8); PG8_WAIT_L(0); PG8_BAR; PG8_MMA(1, 0, At, B0); PG8_MMA(1, 1, At, B1); PG8_BAR; PG8_SCHED;
;             PG8_LDB(B0, 1, 0); PG8_LDB(B1, 1, 1); PG8_SCHED; PG8_LDA(At, 1, 0); PG8_STAGE(PG8_SA(0, 1), a2 + hstepA, voffA);
;             PG8_WAIT_V(8); PG8_WAIT_L(0); PG8_BAR; PG8_MMA(0, 0, At, B0); PG8_MMA(0, 1, At, B1); PG8_BAR; PG8_SCHED;
	v_mfma_f32_16x16x32_bf16 v[60:63], v[128:131], v[184:187], v[60:63]
	v_mfma_f32_16x16x32_bf16 v[56:59], v[136:139], v[184:187], v[56:59]
	v_mfma_f32_16x16x32_bf16 v[52:55], v[128:131], v[198:201], v[52:55]
	v_mfma_f32_16x16x32_bf16 v[44:47], v[136:139], v[198:201], v[44:47]
	v_mfma_f32_16x16x32_bf16 v[36:39], v[128:131], v[216:219], v[36:39]
	v_mfma_f32_16x16x32_bf16 v[28:31], v[136:139], v[216:219], v[28:31]
	v_mfma_f32_16x16x32_bf16 v[20:23], v[128:131], v[224:227], v[20:23]
	v_mfma_f32_16x16x32_bf16 v[12:15], v[136:139], v[224:227], v[12:15]
	v_mfma_f32_16x16x32_bf16 v[60:63], v[132:135], v[188:191], v[60:63]
	v_mfma_f32_16x16x32_bf16 v[56:59], v[140:143], v[188:191], v[56:59]
	v_mfma_f32_16x16x32_bf16 v[52:55], v[132:135], v[202:205], v[52:55]
	v_mfma_f32_16x16x32_bf16 v[44:47], v[140:143], v[202:205], v[44:47]
	v_mfma_f32_16x16x32_bf16 v[36:39], v[132:135], v[220:223], v[36:39]
	v_mfma_f32_16x16x32_bf16 v[28:31], v[140:143], v[220:223], v[28:31]
	v_mfma_f32_16x16x32_bf16 v[20:23], v[132:135], v[228:231], v[20:23]
	v_mfma_f32_16x16x32_bf16 v[12:15], v[140:143], v[228:231], v[12:15]
	v_mfma_f32_16x16x32_bf16 v[48:51], v[168:171], v[184:187], v[48:51]
	v_mfma_f32_16x16x32_bf16 v[40:43], v[176:179], v[184:187], v[40:43]
	v_mfma_f32_16x16x32_bf16 v[32:35], v[168:171], v[198:201], v[32:35]
	v_mfma_f32_16x16x32_bf16 v[24:27], v[176:179], v[198:201], v[24:27]
	v_mfma_f32_16x16x32_bf16 v[16:19], v[168:171], v[216:219], v[16:19]
	v_mfma_f32_16x16x32_bf16 v[8:11], v[176:179], v[216:219], v[8:11]
	v_mfma_f32_16x16x32_bf16 v[4:7], v[168:171], v[224:227], v[4:7]
	v_mfma_f32_16x16x32_bf16 v[0:3], v[176:179], v[224:227], v[0:3]
	v_mfma_f32_16x16x32_bf16 v[48:51], v[172:175], v[188:191], v[48:51]
	v_mfma_f32_16x16x32_bf16 v[40:43], v[180:183], v[188:191], v[40:43]
	v_mfma_f32_16x16x32_bf16 v[32:35], v[172:175], v[202:205], v[32:35]
	v_mfma_f32_16x16x32_bf16 v[24:27], v[180:183], v[202:205], v[24:27]
	v_mfma_f32_16x16x32_bf16 v[16:19], v[172:175], v[220:223], v[16:19]
	v_mfma_f32_16x16x32_bf16 v[8:11], v[180:183], v[220:223], v[8:11]
	v_mfma_f32_16x16x32_bf16 v[4:7], v[172:175], v[228:231], v[4:7]
	v_mfma_f32_16x16x32_bf16 v[0:3], v[180:183], v[228:231], v[0:3]
	s_barrier
	s_add_i32 s52, 0, 0x18000
	s_add_i32 s53, 0, 0x1c000
	v_add_u32_e32 v140, s52, v163
	v_add_u32_e32 v180, s53, v163
	ds_read_b128 v[128:131], v140
	ds_read_b128 v[132:135], v140 offset:1024
	ds_read_b128 v[136:139], v140 offset:2048
	ds_read_b128 v[140:143], v140 offset:3072
	ds_read_b128 v[168:171], v180
	ds_read_b128 v[172:175], v180 offset:1024
	ds_read_b128 v[176:179], v180 offset:2048
	ds_read_b128 v[180:183], v180 offset:3072
	s_add_u32 s26, s26, 0x20000
	s_addc_u32 s27, s27, 0
	s_mov_b32 m0, s31
	v_lshl_add_u64 v[232:233], s[26:27], 0, v[144:145]
	ds_read_b128 v[184:187], v167 offset:32768
	ds_read_b128 v[188:191], v167 offset:33792
	ds_read_b128 v[198:201], v167 offset:34816
	ds_read_b128 v[202:205], v167 offset:35840
	ds_read_b128 v[216:219], v167 offset:36864
	ds_read_b128 v[220:223], v167 offset:37888
	ds_read_b128 v[224:227], v167 offset:38912
	ds_read_b128 v[228:231], v167 offset:39936
	global_load_lds_dwordx4 v[232:233], off
	v_lshl_add_u64 v[232:233], s[26:27], 0, v[148:149]
	s_mov_b32 m0, s34
	s_nop 0
	global_load_lds_dwordx4 v[232:233], off
	s_waitcnt vmcnt(8)
	s_waitcnt lgkmcnt(0)
	s_setprio 1
	s_barrier
	v_mfma_f32_16x16x32_bf16 v[124:127], v[128:131], v[184:187], v[124:127]
	v_mfma_f32_16x16x32_bf16 v[120:123], v[136:139], v[184:187], v[120:123]
	v_mfma_f32_16x16x32_bf16 v[116:119], v[128:131], v[198:201], v[116:119]
	v_mfma_f32_16x16x32_bf16 v[112:115], v[136:139], v[198:201], v[112:115]
	v_mfma_f32_16x16x32_bf16 v[108:111], v[128:131], v[216:219], v[108:111]
	v_mfma_f32_16x16x32_bf16 v[100:103], v[136:139], v[216:219], v[100:103]
	v_mfma_f32_16x16x32_bf16 v[80:83], v[128:131], v[224:227], v[80:83]
	v_mfma_f32_16x16x32_bf16 v[72:75], v[136:139], v[224:227], v[72:75]
	v_mfma_f32_16x16x32_bf16 v[124:127], v[132:135], v[188:191], v[124:127]
	v_mfma_f32_16x16x32_bf16 v[120:123], v[140:143], v[188:191], v[120:123]
	v_mfma_f32_16x16x32_bf16 v[116:119], v[132:135], v[202:205], v[116:119]
	v_mfma_f32_16x16x32_bf16 v[112:115], v[140:143], v[202:205], v[112:115]
	v_mfma_f32_16x16x32_bf16 v[108:111], v[132:135], v[220:223], v[108:111]
	v_mfma_f32_16x16x32_bf16 v[100:103], v[140:143], v[220:223], v[100:103]
	v_mfma_f32_16x16x32_bf16 v[80:83], v[132:135], v[228:231], v[80:83]
	v_mfma_f32_16x16x32_bf16 v[72:75], v[140:143], v[228:231], v[72:75]
	v_mfma_f32_16x16x32_bf16 v[104:107], v[168:171], v[184:187], v[104:107]
	v_mfma_f32_16x16x32_bf16 v[96:99], v[176:179], v[184:187], v[96:99]
	v_mfma_f32_16x16x32_bf16 v[92:95], v[168:171], v[198:201], v[92:95]
	v_mfma_f32_16x16x32_bf16 v[88:91], v[176:179], v[198:201], v[88:91]
	v_mfma_f32_16x16x32_bf16 v[84:87], v[168:171], v[216:219], v[84:87]
	v_mfma_f32_16x16x32_bf16 v[76:79], v[176:179], v[216:219], v[76:79]
	v_mfma_f32_16x16x32_bf16 v[68:71], v[168:171], v[224:227], v[68:71]
	v_mfma_f32_16x16x32_bf16 v[64:67], v[176:179], v[224:227], v[64:67]
	v_mfma_f32_16x16x32_bf16 v[104:107], v[172:175], v[188:191], v[104:107]
	v_mfma_f32_16x16x32_bf16 v[96:99], v[180:183], v[188:191], v[96:99]
	v_mfma_f32_16x16x32_bf16 v[92:95], v[172:175], v[202:205], v[92:95]
	v_mfma_f32_16x16x32_bf16 v[88:91], v[180:183], v[202:205], v[88:91]
	v_mfma_f32_16x16x32_bf16 v[84:87], v[172:175], v[220:223], v[84:87]
	v_mfma_f32_16x16x32_bf16 v[76:79], v[180:183], v[220:223], v[76:79]
	v_mfma_f32_16x16x32_bf16 v[68:71], v[172:175], v[228:231], v[68:71]
	v_mfma_f32_16x16x32_bf16 v[64:67], v[180:183], v[228:231], v[64:67]
	s_barrier
; #define PG8_STAGE(bufoff, gbase, voff) do { _Pragma("unroll") for (int _i = 0; _i < 2; ++_i) \
;         __builtin_amdgcn_global_load_lds((const unsigned*)((const char*)(gbase) + (voff)[_i]), (LAS unsigned*)(lds + (bufoff) + ldsw + _i * 8192), 16, 0, 0); } while (0)
; #define PG8_LDA(dst, b, h) do { _Pragma("unroll") for (int m = 0; m < 4; ++m) _Pragma("unroll") for (int k = 0; k < 2; ++k) dst[m][k] = *(const LAS bf16x8*)(lds + PG8_SA(b, h) + aoff + m * 2048 + k * 1024); } while (0)
; #define PG8_MMA(ai, bj, At, Bt) do { __builtin_amdgcn_s_setprio(1); _Pragma("unroll") for (int m = 0; m < 4; ++m) _Pragma("unroll") for (int n = 0; n < 2; ++n) _Pragma("unroll") for (int k = 0; k < 2; ++k) \
;         acc[ai][bj][m][n] = __builtin_amdgcn_mfma_f32_16x16x32_bf16(Bt[n][k], At[m][k], acc[ai][bj][m][n], 0, 0, 0); __builtin_amdgcn_s_setprio(0); } while (0)
; #define PG8_WAIT_V(n) asm volatile("s_waitcnt vmcnt(" #n ")" ::: "memory")
; #define PG8_WAIT_L(n) asm volatile("s_waitcnt lgkmcnt(" #n ")" ::: "memory")
; #define PG8_BAR __builtin_amdgcn_s_barrier()
; #define PG8_SCHED __builtin_amdgcn_sched_barrier(0)
; template <class Epi, bool ALIGN_EPI, bool SP2 = PG8_SP2_DEFAULT>
; __device__ __forceinline__ void gemm_phase(LAS unsigned char* lds, const Gemm g, const StaticOrder& S, const Epi& E) {
;     ...
;             PG8_LDA(At, 1, 1); PG8_STAGE(PG8_SB(1, 0), b3, voffB); PG8_STAGE(PG8_SB(1, 1), b3 + hstepB, voffB); PG8_STAGE(PG8_SA(1, 0), a3, voffA);
;             PG8_WAIT_V(8); PG8_WAIT_L(0); PG8_BAR; PG8_MMA(1, 0, At, B0); PG8_MMA(1, 1, At, B1); PG8_BAR; PG8_SCHED;
;     ...
;         if constexpr (ALIGN_EPI) { if (wr == 0) PG8_BAR; }
	s_setprio 0
	s_add_i32 s26, s52, s29
	v_lshl_add_u64 v[160:161], v[160:161], 0, s[4:5]
	s_mov_b32 m0, s26
	ds_read_b128 v[184:187], v167 offset:49152
	ds_read_b128 v[188:191], v167 offset:50176
	ds_read_b128 v[198:201], v167 offset:51200
	ds_read_b128 v[202:205], v167 offset:52224
	ds_read_b128 v[216:219], v167 offset:53248
	ds_read_b128 v[220:223], v167 offset:54272
	ds_read_b128 v[224:227], v167 offset:55296
	ds_read_b128 v[228:231], v167 offset:56320
	global_load_lds_dwordx4 v[160:161], off
	s_add_i32 m0, s26, 0x2000
	s_add_u32 s24, s24, 0x20080
	v_lshl_add_u64 v[160:161], v[192:193], 0, s[4:5]
	s_addc_u32 s25, s25, 0
	s_add_i32 s26, s53, s29
	global_load_lds_dwordx4 v[160:161], off
	v_lshl_add_u64 v[160:161], s[24:25], 0, v[146:147]
	s_mov_b32 m0, s26
	s_nop 0
	global_load_lds_dwordx4 v[160:161], off
	v_lshl_add_u64 v[160:161], s[24:25], 0, v[150:151]
	s_add_i32 m0, s26, 0x2000
	s_nop 0
	global_load_lds_dwordx4 v[160:161], off
	v_lshl_add_u64 v[160:161], v[206:207], 0, s[4:5]
	s_mov_b32 m0, s36
	s_nop 0
	global_load_lds_dwordx4 v[160:161], off
	v_lshl_add_u64 v[160:161], v[210:211], 0, s[4:5]
	s_mov_b32 m0, s37
	s_nop 0
	global_load_lds_dwordx4 v[160:161], off
	s_waitcnt vmcnt(8)
	s_waitcnt lgkmcnt(0)
	s_setprio 1
	s_barrier
	v_mfma_f32_16x16x32_bf16 v[60:63], v[128:131], v[184:187], v[60:63]
	v_mfma_f32_16x16x32_bf16 v[56:59], v[136:139], v[184:187], v[56:59]
	v_mfma_f32_16x16x32_bf16 v[52:55], v[128:131], v[198:201], v[52:55]
	v_mfma_f32_16x16x32_bf16 v[44:47], v[136:139], v[198:201], v[44:47]
	v_mfma_f32_16x16x32_bf16 v[36:39], v[128:131], v[216:219], v[36:39]
	v_mfma_f32_16x16x32_bf16 v[28:31], v[136:139], v[216:219], v[28:31]
	v_mfma_f32_16x16x32_bf16 v[20:23], v[128:131], v[224:227], v[20:23]
	v_mfma_f32_16x16x32_bf16 v[12:15], v[136:139], v[224:227], v[12:15]
	v_mfma_f32_16x16x32_bf16 v[60:63], v[132:135], v[188:191], v[60:63]
	v_mfma_f32_16x16x32_bf16 v[56:59], v[140:143], v[188:191], v[56:59]
	v_mfma_f32_16x16x32_bf16 v[52:55], v[132:135], v[202:205], v[52:55]
	v_mfma_f32_16x16x32_bf16 v[44:47], v[140:143], v[202:205], v[44:47]
	v_mfma_f32_16x16x32_bf16 v[36:39], v[132:135], v[220:223], v[36:39]
	v_mfma_f32_16x16x32_bf16 v[28:31], v[140:143], v[220:223], v[28:31]
	v_mfma_f32_16x16x32_bf16 v[20:23], v[132:135], v[228:231], v[20:23]
	v_mfma_f32_16x16x32_bf16 v[12:15], v[140:143], v[228:231], v[12:15]
	v_mfma_f32_16x16x32_bf16 v[48:51], v[168:171], v[184:187], v[48:51]
	v_mfma_f32_16x16x32_bf16 v[40:43], v[176:179], v[184:187], v[40:43]
	v_mfma_f32_16x16x32_bf16 v[32:35], v[168:171], v[198:201], v[32:35]
	v_mfma_f32_16x16x32_bf16 v[24:27], v[176:179], v[198:201], v[24:27]
	v_mfma_f32_16x16x32_bf16 v[16:19], v[168:171], v[216:219], v[16:19]
	v_mfma_f32_16x16x32_bf16 v[8:11], v[176:179], v[216:219], v[8:11]
	v_mfma_f32_16x16x32_bf16 v[4:7], v[168:171], v[224:227], v[4:7]
	v_mfma_f32_16x16x32_bf16 v[0:3], v[176:179], v[224:227], v[0:3]
	v_mfma_f32_16x16x32_bf16 v[48:51], v[172:175], v[188:191], v[48:51]
	v_mfma_f32_16x16x32_bf16 v[40:43], v[180:183], v[188:191], v[40:43]
	v_mfma_f32_16x16x32_bf16 v[32:35], v[172:175], v[202:205], v[32:35]
	v_mfma_f32_16x16x32_bf16 v[24:27], v[180:183], v[202:205], v[24:27]
	v_mfma_f32_16x16x32_bf16 v[16:19], v[172:175], v[220:223], v[16:19]
	v_mfma_f32_16x16x32_bf16 v[8:11], v[180:183], v[220:223], v[8:11]
	v_mfma_f32_16x16x32_bf16 v[4:7], v[172:175], v[228:231], v[4:7]
	v_mfma_f32_16x16x32_bf16 v[0:3], v[180:183], v[228:231], v[0:3]
	s_barrier
	s_add_i32 s51, s51, 2
	s_add_u32 s22, s22, 0x100
	s_addc_u32 s23, s23, 0
	s_add_u32 s49, s49, 0x100
	s_addc_u32 s50, s50, 0
	s_cmp_gt_u32 s51, 5
	s_cbranch_scc0 .LBB0_428
	s_and_b64 vcc, exec, s[6:7]
	s_cbranch_vccz .LBB0_431
	s_barrier

; #define PG8_STAGE(bufoff, gbase, voff) do { _Pragma("unroll") for (int _i = 0; _i < 2; ++_i) \
;         __builtin_amdgcn_global_load_lds((const unsigned*)((const char*)(gbase) + (voff)[_i]), (LAS unsigned*)(lds + (bufoff) + ldsw + _i * 8192), 16, 0, 0); } while (0)
; #define PG8_LDA(dst, b, h) do { _Pragma("unroll") for (int m = 0; m < 4; ++m) _Pragma("unroll") for (int k = 0; k < 2; ++k) dst[m][k] = *(const LAS bf16x8*)(lds + PG8_SA(b, h) + aoff + m * 2048 + k * 1024); } while (0)
; #define PG8_LDB(dst, b, h) do { _Pragma("unroll") for (int n = 0; n < 2; ++n) _Pragma("unroll") for (int k = 0; k < 2; ++k) dst[n][k] = *(const LAS bf16x8*)(lds + PG8_SB(b, h) + boff + n * 2048 + k * 1024); } while (0)
; #define PG8_MMA(ai, bj, At, Bt) do { __builtin_amdgcn_s_setprio(1); _Pragma("unroll") for (int m = 0; m < 4; ++m) _Pragma("unroll") for (int n = 0; n < 2; ++n) _Pragma("unroll") for (int k = 0; k < 2; ++k) \
;         acc[ai][bj][m][n] = __builtin_amdgcn_mfma_f32_16x16x32_bf16(Bt[n][k], At[m][k], acc[ai][bj][m][n], 0, 0, 0); __builtin_amdgcn_s_setprio(0); } while (0)
; #define PG8_WAIT_V(n) asm volatile("s_waitcnt vmcnt(" #n ")" ::: "memory")
; template <class Epi, bool ALIGN_EPI, bool SP2 = PG8_SP2_DEFAULT>
; __device__ __forceinline__ void gemm_phase(LAS unsigned char* lds, const Gemm g, const StaticOrder& S, const Epi& E) {
;     ...
;         const char* nA = has_next ? PG8_ABASE(nxt) : cA; const char* nB = has_next ? (const char*)g.Bt + (size_t)nxt.pn * tstepB : cB;
;         for (int t = 0; t < nt; t += 2) {
;             const bool last = (t == nt - 2);
;             const char* a1 = cA + (size_t)(t + 1) * kstep;
;             const char* a2 = last ? nA : cA + (size_t)(t + 2) * kstep; const char* b2 = last ? nB : cB + (size_t)(t + 2) * kstep;
;             const char* a3 = a2 + kstep; const char* b3 = b2 + kstep;
;             if constexpr (SP2) {
;             PG8_LDB(B0, 0, 0); PG8_LDB(B1, 0, 1); PG8_SCHED; PG8_LDA(At, 0, 0); PG8_STAGE(PG8_SA(1, 1), a1 + hstepA, voffA);
;             PG8_WAIT_V(8); PG8_WAIT_L(0); PG8_BAR; PG8_MMA(0, 0, At, B0); PG8_MMA(0, 1, At, B1); PG8_BAR; PG8_SCHED;
;             PG8_LDA(At, 0, 1); PG8_STAGE(PG8_SB(0, 0), b2, voffB); PG8_STAGE(PG8_SB(0, 1), b2 + hstepB, voffB); PG8_STAGE(PG8_SA(0, 0), a2, voffA);
;             PG8_WAIT_V(8); PG8_WAIT_L(0); PG8_BAR; PG8_MMA(1, 0, At, B0); PG8_MMA(1, 1, At, B1); PG8_BAR; PG8_SCHED;
.LBB0_506:
	ds_read_b128 v[144:147], v151
	ds_read_b128 v[156:159], v151 offset:1024
	ds_read_b128 v[160:163], v151 offset:2048
	ds_read_b128 v[164:167], v151 offset:3072
	ds_read_b128 v[168:171], v152
	ds_read_b128 v[172:175], v152 offset:1024
	ds_read_b128 v[176:179], v152 offset:2048
	ds_read_b128 v[180:183], v152 offset:3072
	s_add_u32 s28, s26, 0xfff00080
	s_addc_u32 s29, s27, -1
	s_cmp_eq_u32 s50, 60
	s_cselect_b32 s31, s19, s29
	s_cselect_b32 s30, s25, s28
	s_cselect_b32 s29, s3, s49
	s_cselect_b32 s28, s47, s48
	v_lshl_add_u64 v[192:193], s[26:27], 0, v[136:137]
	s_add_i32 m0, s34, 0xc000
	ds_read_b128 v[184:187], v153
	ds_read_b128 v[188:191], v153 offset:1024
	ds_read_b128 v[198:201], v153 offset:2048
	ds_read_b128 v[202:205], v153 offset:3072
	ds_read_b128 v[216:219], v153 offset:4096
	ds_read_b128 v[220:223], v153 offset:5120
	ds_read_b128 v[224:227], v153 offset:6144
	ds_read_b128 v[228:231], v153 offset:7168
	global_load_lds_dwordx4 v[192:193], off
	v_lshl_add_u64 v[192:193], s[26:27], 0, v[138:139]
	s_add_i32 m0, s34, 0xe000
	s_nop 0
	global_load_lds_dwordx4 v[192:193], off
	s_waitcnt vmcnt(8)
	s_waitcnt lgkmcnt(0)
	s_setprio 1
	s_barrier
	v_mfma_f32_16x16x32_bf16 v[124:127], v[144:147], v[184:187], v[124:127]
	v_mfma_f32_16x16x32_bf16 v[120:123], v[160:163], v[184:187], v[120:123]
	v_mfma_f32_16x16x32_bf16 v[108:111], v[144:147], v[198:201], v[108:111]
	v_mfma_f32_16x16x32_bf16 v[104:107], v[160:163], v[198:201], v[104:107]
	v_mfma_f32_16x16x32_bf16 v[92:95], v[144:147], v[216:219], v[92:95]
	v_mfma_f32_16x16x32_bf16 v[88:91], v[160:163], v[216:219], v[88:91]
	v_mfma_f32_16x16x32_bf16 v[76:79], v[144:147], v[224:227], v[76:79]
	v_mfma_f32_16x16x32_bf16 v[72:75], v[160:163], v[224:227], v[72:75]
	v_mfma_f32_16x16x32_bf16 v[124:127], v[156:159], v[188:191], v[124:127]
	v_mfma_f32_16x16x32_bf16 v[120:123], v[164:167], v[188:191], v[120:123]
	v_mfma_f32_16x16x32_bf16 v[108:111], v[156:159], v[202:205], v[108:111]
	v_mfma_f32_16x16x32_bf16 v[104:107], v[164:167], v[202:205], v[104:107]
	v_mfma_f32_16x16x32_bf16 v[92:95], v[156:159], v[220:223], v[92:95]
	v_mfma_f32_16x16x32_bf16 v[88:91], v[164:167], v[220:223], v[88:91]
	v_mfma_f32_16x16x32_bf16 v[76:79], v[156:159], v[228:231], v[76:79]
	v_mfma_f32_16x16x32_bf16 v[72:75], v[164:167], v[228:231], v[72:75]
	v_mfma_f32_16x16x32_bf16 v[116:119], v[168:171], v[184:187], v[116:119]
	v_mfma_f32_16x16x32_bf16 v[112:115], v[176:179], v[184:187], v[112:115]
	v_mfma_f32_16x16x32_bf16 v[100:103], v[168:171], v[198:201], v[100:103]
	v_mfma_f32_16x16x32_bf16 v[96:99], v[176:179], v[198:201], v[96:99]
	v_mfma_f32_16x16x32_bf16 v[84:87], v[168:171], v[216:219], v[84:87]
	v_mfma_f32_16x16x32_bf16 v[80:83], v[176:179], v[216:219], v[80:83]
	v_mfma_f32_16x16x32_bf16 v[68:71], v[168:171], v[224:227], v[68:71]
	v_mfma_f32_16x16x32_bf16 v[64:67], v[176:179], v[224:227], v[64:67]
	v_mfma_f32_16x16x32_bf16 v[116:119], v[172:175], v[188:191], v[116:119]
	v_mfma_f32_16x16x32_bf16 v[112:115], v[180:183], v[188:191], v[112:115]
	v_mfma_f32_16x16x32_bf16 v[100:103], v[172:175], v[202:205], v[100:103]
	v_mfma_f32_16x16x32_bf16 v[96:99], v[180:183], v[202:205], v[96:99]
	v_mfma_f32_16x16x32_bf16 v[84:87], v[172:175], v[220:223], v[84:87]
	v_mfma_f32_16x16x32_bf16 v[80:83], v[180:183], v[220:223], v[80:83]
	v_mfma_f32_16x16x32_bf16 v[68:71], v[172:175], v[228:231], v[68:71]
	v_mfma_f32_16x16x32_bf16 v[64:67], v[180:183], v[228:231], v[64:67]
	s_barrier
	s_setprio 0
	s_add_i32 s51, s44, s33
	v_lshl_add_u64 v[192:193], s[28:29], 0, v[130:131]
	s_mov_b32 m0, s51
	ds_read_b128 v[184:187], v153 offset:16384
	ds_read_b128 v[188:191], v153 offset:17408
	ds_read_b128 v[198:201], v153 offset:18432
	ds_read_b128 v[202:205], v153 offset:19456
	ds_read_b128 v[216:219], v153 offset:20480
	ds_read_b128 v[220:223], v153 offset:21504
	ds_read_b128 v[224:227], v153 offset:22528
	ds_read_b128 v[228:231], v153 offset:23552
	global_load_lds_dwordx4 v[192:193], off
	s_add_i32 m0, s51, 0x2000
	s_add_u32 s52, s28, 0x100000
	v_lshl_add_u64 v[206:207], s[28:29], 0, v[134:135]
	s_addc_u32 s53, s29, 0
	s_add_i32 s51, s45, s33
	global_load_lds_dwordx4 v[206:207], off
	v_lshl_add_u64 v[210:211], s[52:53], 0, v[130:131]
	s_mov_b32 m0, s51
	v_lshl_add_u64 v[232:233], s[30:31], 0, v[132:133]
	global_load_lds_dwordx4 v[210:211], off
	v_lshl_add_u64 v[210:211], s[52:53], 0, v[134:135]
	s_add_i32 m0, s51, 0x2000
	s_nop 0
	global_load_lds_dwordx4 v[210:211], off
	v_lshl_add_u64 v[210:211], s[30:31], 0, v[128:129]
	s_mov_b32 m0, s34
	s_nop 0
	global_load_lds_dwordx4 v[210:211], off
	s_mov_b32 m0, s35
	s_nop 0
	global_load_lds_dwordx4 v[232:233], off
	s_waitcnt vmcnt(8)
	s_waitcnt lgkmcnt(0)
	s_setprio 1
	s_barrier
; #define PG8_STAGE(bufoff, gbase, voff) do { _Pragma("unroll") for (int _i = 0; _i < 2; ++_i) \
;         __builtin_amdgcn_global_load_lds((const unsigned*)((const char*)(gbase) + (voff)[_i]), (LAS unsigned*)(lds + (bufoff) + ldsw + _i * 8192), 16, 0, 0); } while (0)
; #define PG8_LDA(dst, b, h) do { _Pragma("unroll") for (int m = 0; m < 4; ++m) _Pragma("unroll") for (int k = 0; k < 2; ++k) dst[m][k] = *(const LAS bf16x8*)(lds + PG8_SA(b, h) + aoff + m * 2048 + k * 1024); } while (0)
; #define PG8_LDB(dst, b, h) do { _Pragma("unroll") for (int n = 0; n < 2; ++n) _Pragma("unroll") for (int k = 0; k < 2; ++k) dst[n][k] = *(const LAS bf16x8*)(lds + PG8_SB(b, h) + boff + n * 2048 + k * 1024); } while (0)
; #define PG8_MMA(ai, bj, At, Bt) do { __builtin_amdgcn_s_setprio(1); _Pragma("unroll") for (int m = 0; m < 4; ++m) _Pragma("unroll") for (int n = 0; n < 2; ++n) _Pragma("unroll") for (int k = 0; k < 2; ++k) \
;         acc[ai][bj][m][n] = __builtin_amdgcn_mfma_f32_16x16x32_bf16(Bt[n][k], At[m][k], acc[ai][bj][m][n], 0, 0, 0); __builtin_amdgcn_s_setprio(0); } while (0)
; #define PG8_WAIT_V(n) asm volatile("s_waitcnt vmcnt(" #n ")" ::: "memory")
; #define PG8_WAIT_L(n) asm volatile("s_waitcnt lgkmcnt(" #n ")" ::: "memory")
; #define PG8_BAR __builtin_amdgcn_s_barrier()
; #define PG8_SCHED __builtin_amdgcn_sched_barrier(0)
; template <class Epi, bool ALIGN_EPI, bool SP2 = PG8_SP2_DEFAULT>
; __device__ __forceinline__ void gemm_phase(LAS unsigned char* lds, const Gemm g, const StaticOrder& S, const Epi& E) {
;     ...
;             PG8_WAIT_V(8); PG8_WAIT_L(0); PG8_BAR; PG8_MMA(1, 0, At, B0); PG8_MMA(1, 1, At, B1); PG8_BAR; PG8_SCHED;
;             PG8_LDB(B0, 1, 0); PG8_LDB(B1, 1, 1); PG8_SCHED; PG8_LDA(At, 1, 0); PG8_STAGE(PG8_SA(0, 1), a2 + hstepA, voffA);
;             PG8_WAIT_V(8); PG8_WAIT_L(0); PG8_BAR; PG8_MMA(0, 0, At, B0); PG8_MMA(0, 1, At, B1); PG8_BAR; PG8_SCHED;
	v_mfma_f32_16x16x32_bf16 v[60:63], v[144:147], v[184:187], v[60:63]
	v_mfma_f32_16x16x32_bf16 v[56:59], v[160:163], v[184:187], v[56:59]
	v_mfma_f32_16x16x32_bf16 v[44:47], v[144:147], v[198:201], v[44:47]
	v_mfma_f32_16x16x32_bf16 v[40:43], v[160:163], v[198:201], v[40:43]
	v_mfma_f32_16x16x32_bf16 v[28:31], v[144:147], v[216:219], v[28:31]
	v_mfma_f32_16x16x32_bf16 v[24:27], v[160:163], v[216:219], v[24:27]
	v_mfma_f32_16x16x32_bf16 v[12:15], v[144:147], v[224:227], v[12:15]
	v_mfma_f32_16x16x32_bf16 v[8:11], v[160:163], v[224:227], v[8:11]
	v_mfma_f32_16x16x32_bf16 v[60:63], v[156:159], v[188:191], v[60:63]
	v_mfma_f32_16x16x32_bf16 v[56:59], v[164:167], v[188:191], v[56:59]
	v_mfma_f32_16x16x32_bf16 v[44:47], v[156:159], v[202:205], v[44:47]
	v_mfma_f32_16x16x32_bf16 v[40:43], v[164:167], v[202:205], v[40:43]
	v_mfma_f32_16x16x32_bf16 v[28:31], v[156:159], v[220:223], v[28:31]
	v_mfma_f32_16x16x32_bf16 v[24:27], v[164:167], v[220:223], v[24:27]
	v_mfma_f32_16x16x32_bf16 v[12:15], v[156:159], v[228:231], v[12:15]
	v_mfma_f32_16x16x32_bf16 v[8:11], v[164:167], v[228:231], v[8:11]
	v_mfma_f32_16x16x32_bf16 v[52:55], v[168:171], v[184:187], v[52:55]
	v_mfma_f32_16x16x32_bf16 v[48:51], v[176:179], v[184:187], v[48:51]
	v_mfma_f32_16x16x32_bf16 v[36:39], v[168:171], v[198:201], v[36:39]
	v_mfma_f32_16x16x32_bf16 v[32:35], v[176:179], v[198:201], v[32:35]
	v_mfma_f32_16x16x32_bf16 v[20:23], v[168:171], v[216:219], v[20:23]
	v_mfma_f32_16x16x32_bf16 v[16:19], v[176:179], v[216:219], v[16:19]
	v_mfma_f32_16x16x32_bf16 v[4:7], v[168:171], v[224:227], v[4:7]
	v_mfma_f32_16x16x32_bf16 v[0:3], v[176:179], v[224:227], v[0:3]
	v_mfma_f32_16x16x32_bf16 v[52:55], v[172:175], v[188:191], v[52:55]
	v_mfma_f32_16x16x32_bf16 v[48:51], v[180:183], v[188:191], v[48:51]
	v_mfma_f32_16x16x32_bf16 v[36:39], v[172:175], v[202:205], v[36:39]
	v_mfma_f32_16x16x32_bf16 v[32:35], v[180:183], v[202:205], v[32:35]
	v_mfma_f32_16x16x32_bf16 v[20:23], v[172:175], v[220:223], v[20:23]
	v_mfma_f32_16x16x32_bf16 v[16:19], v[180:183], v[220:223], v[16:19]
	v_mfma_f32_16x16x32_bf16 v[4:7], v[172:175], v[228:231], v[4:7]
	v_mfma_f32_16x16x32_bf16 v[0:3], v[180:183], v[228:231], v[0:3]
	s_barrier
	s_add_i32 s51, 0, 0x18000
	v_add_u32_e32 v155, s51, v149
	s_add_i32 s52, 0, 0x1c000
	ds_read_b128 v[144:147], v155
	ds_read_b128 v[156:159], v155 offset:1024
	ds_read_b128 v[160:163], v155 offset:2048
	ds_read_b128 v[164:167], v155 offset:3072
	v_add_u32_e32 v155, s52, v149
	ds_read_b128 v[168:171], v155
	ds_read_b128 v[172:175], v155 offset:1024
	ds_read_b128 v[176:179], v155 offset:2048
	ds_read_b128 v[180:183], v155 offset:3072
	s_add_u32 s30, s30, 0x100000
	s_addc_u32 s31, s31, 0
	s_mov_b32 m0, s36
	v_lshl_add_u64 v[234:235], s[30:31], 0, v[128:129]
	ds_read_b128 v[184:187], v153 offset:32768
	ds_read_b128 v[188:191], v153 offset:33792
	ds_read_b128 v[198:201], v153 offset:34816
	ds_read_b128 v[202:205], v153 offset:35840
	ds_read_b128 v[216:219], v153 offset:36864
	ds_read_b128 v[220:223], v153 offset:37888
	ds_read_b128 v[224:227], v153 offset:38912
	ds_read_b128 v[228:231], v153 offset:39936
	global_load_lds_dwordx4 v[234:235], off
	v_lshl_add_u64 v[234:235], s[30:31], 0, v[132:133]
	s_mov_b32 m0, s37
	s_nop 0
	global_load_lds_dwordx4 v[234:235], off
	s_waitcnt vmcnt(8)
	s_waitcnt lgkmcnt(0)
	s_setprio 1
	s_barrier
	v_mfma_f32_16x16x32_bf16 v[124:127], v[144:147], v[184:187], v[124:127]
	v_mfma_f32_16x16x32_bf16 v[120:123], v[160:163], v[184:187], v[120:123]
	v_mfma_f32_16x16x32_bf16 v[108:111], v[144:147], v[198:201], v[108:111]
	v_mfma_f32_16x16x32_bf16 v[104:107], v[160:163], v[198:201], v[104:107]
	v_mfma_f32_16x16x32_bf16 v[92:95], v[144:147], v[216:219], v[92:95]
	v_mfma_f32_16x16x32_bf16 v[88:91], v[160:163], v[216:219], v[88:91]
	v_mfma_f32_16x16x32_bf16 v[76:79], v[144:147], v[224:227], v[76:79]
	v_mfma_f32_16x16x32_bf16 v[72:75], v[160:163], v[224:227], v[72:75]
	v_mfma_f32_16x16x32_bf16 v[124:127], v[156:159], v[188:191], v[124:127]
	v_mfma_f32_16x16x32_bf16 v[120:123], v[164:167], v[188:191], v[120:123]
	v_mfma_f32_16x16x32_bf16 v[108:111], v[156:159], v[202:205], v[108:111]
	v_mfma_f32_16x16x32_bf16 v[104:107], v[164:167], v[202:205], v[104:107]
	v_mfma_f32_16x16x32_bf16 v[92:95], v[156:159], v[220:223], v[92:95]
	v_mfma_f32_16x16x32_bf16 v[88:91], v[164:167], v[220:223], v[88:91]
	v_mfma_f32_16x16x32_bf16 v[76:79], v[156:159], v[228:231], v[76:79]
	v_mfma_f32_16x16x32_bf16 v[72:75], v[164:167], v[228:231], v[72:75]
	v_mfma_f32_16x16x32_bf16 v[116:119], v[168:171], v[184:187], v[116:119]
	v_mfma_f32_16x16x32_bf16 v[112:115], v[176:179], v[184:187], v[112:115]
	v_mfma_f32_16x16x32_bf16 v[100:103], v[168:171], v[198:201], v[100:103]
	v_mfma_f32_16x16x32_bf16 v[96:99], v[176:179], v[198:201], v[96:99]
	v_mfma_f32_16x16x32_bf16 v[84:87], v[168:171], v[216:219], v[84:87]
	v_mfma_f32_16x16x32_bf16 v[80:83], v[176:179], v[216:219], v[80:83]
	v_mfma_f32_16x16x32_bf16 v[68:71], v[168:171], v[224:227], v[68:71]
	v_mfma_f32_16x16x32_bf16 v[64:67], v[176:179], v[224:227], v[64:67]
	v_mfma_f32_16x16x32_bf16 v[116:119], v[172:175], v[188:191], v[116:119]
	v_mfma_f32_16x16x32_bf16 v[112:115], v[180:183], v[188:191], v[112:115]
	v_mfma_f32_16x16x32_bf16 v[100:103], v[172:175], v[202:205], v[100:103]
	v_mfma_f32_16x16x32_bf16 v[96:99], v[180:183], v[202:205], v[96:99]
	v_mfma_f32_16x16x32_bf16 v[84:87], v[172:175], v[220:223], v[84:87]
	v_mfma_f32_16x16x32_bf16 v[80:83], v[180:183], v[220:223], v[80:83]
	v_mfma_f32_16x16x32_bf16 v[68:71], v[172:175], v[228:231], v[68:71]
	v_mfma_f32_16x16x32_bf16 v[64:67], v[180:183], v[228:231], v[64:67]
	s_barrier
; #define PG8_STAGE(bufoff, gbase, voff) do { _Pragma("unroll") for (int _i = 0; _i < 2; ++_i) \
;         __builtin_amdgcn_global_load_lds((const unsigned*)((const char*)(gbase) + (voff)[_i]), (LAS unsigned*)(lds + (bufoff) + ldsw + _i * 8192), 16, 0, 0); } while (0)
; #define PG8_LDA(dst, b, h) do { _Pragma("unroll") for (int m = 0; m < 4; ++m) _Pragma("unroll") for (int k = 0; k < 2; ++k) dst[m][k] = *(const LAS bf16x8*)(lds + PG8_SA(b, h) + aoff + m * 2048 + k * 1024); } while (0)
; #define PG8_MMA(ai, bj, At, Bt) do { __builtin_amdgcn_s_setprio(1); _Pragma("unroll") for (int m = 0; m < 4; ++m) _Pragma("unroll") for (int n = 0; n < 2; ++n) _Pragma("unroll") for (int k = 0; k < 2; ++k) \
;         acc[ai][bj][m][n] = __builtin_amdgcn_mfma_f32_16x16x32_bf16(Bt[n][k], At[m][k], acc[ai][bj][m][n], 0, 0, 0); __builtin_amdgcn_s_setprio(0); } while (0)
; #define PG8_WAIT_V(n) asm volatile("s_waitcnt vmcnt(" #n ")" ::: "memory")
; #define PG8_WAIT_L(n) asm volatile("s_waitcnt lgkmcnt(" #n ")" ::: "memory")
; #define PG8_BAR __builtin_amdgcn_s_barrier()
; #define PG8_SCHED __builtin_amdgcn_sched_barrier(0)
; template <class Epi, bool ALIGN_EPI, bool SP2 = PG8_SP2_DEFAULT>
; __device__ __forceinline__ void gemm_phase(LAS unsigned char* lds, const Gemm g, const StaticOrder& S, const Epi& E) {
;     ...
;             PG8_LDA(At, 1, 1); PG8_STAGE(PG8_SB(1, 0), b3, voffB); PG8_STAGE(PG8_SB(1, 1), b3 + hstepB, voffB); PG8_STAGE(PG8_SA(1, 0), a3, voffA);
;             PG8_WAIT_V(8); PG8_WAIT_L(0); PG8_BAR; PG8_MMA(1, 0, At, B0); PG8_MMA(1, 1, At, B1); PG8_BAR; PG8_SCHED;
;     ...
;         if constexpr (ALIGN_EPI) { if (wr == 0) PG8_BAR; }
	s_setprio 0
	s_add_i32 s30, s51, s33
	v_lshl_add_u64 v[192:193], v[192:193], 0, s[14:15]
	s_mov_b32 m0, s30
	ds_read_b128 v[184:187], v153 offset:49152
	ds_read_b128 v[188:191], v153 offset:50176
	ds_read_b128 v[198:201], v153 offset:51200
	ds_read_b128 v[202:205], v153 offset:52224
	ds_read_b128 v[216:219], v153 offset:53248
	ds_read_b128 v[220:223], v153 offset:54272
	ds_read_b128 v[224:227], v153 offset:55296
	ds_read_b128 v[228:231], v153 offset:56320
	global_load_lds_dwordx4 v[192:193], off
	s_add_i32 m0, s30, 0x2000
	s_add_u32 s28, s28, 0x100080
	v_lshl_add_u64 v[192:193], v[206:207], 0, s[14:15]
	s_addc_u32 s29, s29, 0
	s_add_i32 s30, s52, s33
	global_load_lds_dwordx4 v[192:193], off
	v_lshl_add_u64 v[192:193], s[28:29], 0, v[130:131]
	s_mov_b32 m0, s30
	s_nop 0
	global_load_lds_dwordx4 v[192:193], off
	v_lshl_add_u64 v[192:193], s[28:29], 0, v[134:135]
	s_add_i32 m0, s30, 0x2000
	s_nop 0
	global_load_lds_dwordx4 v[192:193], off
	v_lshl_add_u64 v[192:193], v[210:211], 0, s[14:15]
	s_mov_b32 m0, s39
	s_nop 0
	global_load_lds_dwordx4 v[192:193], off
	v_lshl_add_u64 v[192:193], v[232:233], 0, s[14:15]
	s_mov_b32 m0, s40
	s_nop 0
	global_load_lds_dwordx4 v[192:193], off
	s_waitcnt vmcnt(8)
	s_waitcnt lgkmcnt(0)
	s_setprio 1
	s_barrier
	v_mfma_f32_16x16x32_bf16 v[60:63], v[144:147], v[184:187], v[60:63]
	v_mfma_f32_16x16x32_bf16 v[56:59], v[160:163], v[184:187], v[56:59]
	v_mfma_f32_16x16x32_bf16 v[44:47], v[144:147], v[198:201], v[44:47]
	v_mfma_f32_16x16x32_bf16 v[40:43], v[160:163], v[198:201], v[40:43]
	v_mfma_f32_16x16x32_bf16 v[28:31], v[144:147], v[216:219], v[28:31]
	v_mfma_f32_16x16x32_bf16 v[24:27], v[160:163], v[216:219], v[24:27]
	v_mfma_f32_16x16x32_bf16 v[12:15], v[144:147], v[224:227], v[12:15]
	v_mfma_f32_16x16x32_bf16 v[8:11], v[160:163], v[224:227], v[8:11]
	v_mfma_f32_16x16x32_bf16 v[60:63], v[156:159], v[188:191], v[60:63]
	v_mfma_f32_16x16x32_bf16 v[56:59], v[164:167], v[188:191], v[56:59]
	v_mfma_f32_16x16x32_bf16 v[44:47], v[156:159], v[202:205], v[44:47]
	v_mfma_f32_16x16x32_bf16 v[40:43], v[164:167], v[202:205], v[40:43]
	v_mfma_f32_16x16x32_bf16 v[28:31], v[156:159], v[220:223], v[28:31]
	v_mfma_f32_16x16x32_bf16 v[24:27], v[164:167], v[220:223], v[24:27]
	v_mfma_f32_16x16x32_bf16 v[12:15], v[156:159], v[228:231], v[12:15]
	v_mfma_f32_16x16x32_bf16 v[8:11], v[164:167], v[228:231], v[8:11]
	v_mfma_f32_16x16x32_bf16 v[52:55], v[168:171], v[184:187], v[52:55]
	v_mfma_f32_16x16x32_bf16 v[48:51], v[176:179], v[184:187], v[48:51]
	v_mfma_f32_16x16x32_bf16 v[36:39], v[168:171], v[198:201], v[36:39]
	v_mfma_f32_16x16x32_bf16 v[32:35], v[176:179], v[198:201], v[32:35]
	v_mfma_f32_16x16x32_bf16 v[20:23], v[168:171], v[216:219], v[20:23]
	v_mfma_f32_16x16x32_bf16 v[16:19], v[176:179], v[216:219], v[16:19]
	v_mfma_f32_16x16x32_bf16 v[4:7], v[168:171], v[224:227], v[4:7]
	v_mfma_f32_16x16x32_bf16 v[0:3], v[176:179], v[224:227], v[0:3]
	v_mfma_f32_16x16x32_bf16 v[52:55], v[172:175], v[188:191], v[52:55]
	v_mfma_f32_16x16x32_bf16 v[48:51], v[180:183], v[188:191], v[48:51]
	v_mfma_f32_16x16x32_bf16 v[36:39], v[172:175], v[202:205], v[36:39]
	v_mfma_f32_16x16x32_bf16 v[32:35], v[180:183], v[202:205], v[32:35]
	v_mfma_f32_16x16x32_bf16 v[20:23], v[172:175], v[220:223], v[20:23]
	v_mfma_f32_16x16x32_bf16 v[16:19], v[180:183], v[220:223], v[16:19]
	v_mfma_f32_16x16x32_bf16 v[4:7], v[172:175], v[228:231], v[4:7]
	v_mfma_f32_16x16x32_bf16 v[0:3], v[180:183], v[228:231], v[0:3]
	s_barrier
	s_add_i32 s50, s50, 2
	s_add_u32 s26, s26, 0x100
	s_addc_u32 s27, s27, 0
	s_add_u32 s48, s48, 0x100
	s_addc_u32 s49, s49, 0
	s_cmp_gt_u32 s50, 61
	s_cbranch_scc0 .LBB0_506
	s_and_b64 vcc, exec, s[16:17]
	s_cbranch_vccz .LBB0_509
	s_barrier

; #define PG8_STAGE(bufoff, gbase, voff) do { _Pragma("unroll") for (int _i = 0; _i < 2; ++_i) \
;         __builtin_amdgcn_global_load_lds((const unsigned*)((const char*)(gbase) + (voff)[_i]), (LAS unsigned*)(lds + (bufoff) + ldsw + _i * 8192), 16, 0, 0); } while (0)
; #define PG8_LDA(dst, b, h) do { _Pragma("unroll") for (int m = 0; m < 4; ++m) _Pragma("unroll") for (int k = 0; k < 2; ++k) dst[m][k] = *(const LAS bf16x8*)(lds + PG8_SA(b, h) + aoff + m * 2048 + k * 1024); } while (0)
; #define PG8_LDB(dst, b, h) do { _Pragma("unroll") for (int n = 0; n < 2; ++n) _Pragma("unroll") for (int k = 0; k < 2; ++k) dst[n][k] = *(const LAS bf16x8*)(lds + PG8_SB(b, h) + boff + n * 2048 + k * 1024); } while (0)
; #define PG8_MMA(ai, bj, At, Bt) do { __builtin_amdgcn_s_setprio(1); _Pragma("unroll") for (int m = 0; m < 4; ++m) _Pragma("unroll") for (int n = 0; n < 2; ++n) _Pragma("unroll") for (int k = 0; k < 2; ++k) \
;         acc[ai][bj][m][n] = __builtin_amdgcn_mfma_f32_16x16x32_bf16(Bt[n][k], At[m][k], acc[ai][bj][m][n], 0, 0, 0); __builtin_amdgcn_s_setprio(0); } while (0)
; #define PG8_WAIT_V(n) asm volatile("s_waitcnt vmcnt(" #n ")" ::: "memory")
; template <class Epi, bool ALIGN_EPI, bool SP2 = PG8_SP2_DEFAULT>
; __device__ __forceinline__ void gemm_phase(LAS unsigned char* lds, const Gemm g, const StaticOrder& S, const Epi& E) {
;     ...
;         const char* nA = has_next ? PG8_ABASE(nxt) : cA; const char* nB = has_next ? (const char*)g.Bt + (size_t)nxt.pn * tstepB : cB;
;         for (int t = 0; t < nt; t += 2) {
;             const bool last = (t == nt - 2);
;             const char* a1 = cA + (size_t)(t + 1) * kstep;
;             const char* a2 = last ? nA : cA + (size_t)(t + 2) * kstep; const char* b2 = last ? nB : cB + (size_t)(t + 2) * kstep;
;             const char* a3 = a2 + kstep; const char* b3 = b2 + kstep;
;             if constexpr (SP2) {
;             PG8_LDB(B0, 0, 0); PG8_LDB(B1, 0, 1); PG8_SCHED; PG8_LDA(At, 0, 0); PG8_STAGE(PG8_SA(1, 1), a1 + hstepA, voffA);
;             PG8_WAIT_V(8); PG8_WAIT_L(0); PG8_BAR; PG8_MMA(0, 0, At, B0); PG8_MMA(0, 1, At, B1); PG8_BAR; PG8_SCHED;
;             PG8_LDA(At, 0, 1); PG8_STAGE(PG8_SB(0, 0), b2, voffB); PG8_STAGE(PG8_SB(0, 1), b2 + hstepB, voffB); PG8_STAGE(PG8_SA(0, 0), a2, voffA);
;             PG8_WAIT_V(8); PG8_WAIT_L(0); PG8_BAR; PG8_MMA(1, 0, At, B0); PG8_MMA(1, 1, At, B1); PG8_BAR; PG8_SCHED;
.LBB0_598:
	ds_read_b128 v[146:149], v155
	ds_read_b128 v[160:163], v155 offset:1024
	ds_read_b128 v[164:167], v155 offset:2048
	ds_read_b128 v[168:171], v155 offset:3072
	ds_read_b128 v[172:175], v156
	ds_read_b128 v[176:179], v156 offset:1024
	ds_read_b128 v[180:183], v156 offset:2048
	ds_read_b128 v[184:187], v156 offset:3072
	s_add_u32 s24, s22, 0xfff00080
	s_addc_u32 s25, s23, -1
	s_cmp_eq_u32 s47, 60
	s_cselect_b32 s27, s3, s25
	s_cselect_b32 s26, s7, s24
	s_cselect_b32 s25, s9, s45
	s_cselect_b32 s24, s17, s44
	v_lshl_add_u64 v[192:193], s[22:23], 0, v[138:139]
	s_add_i32 m0, s30, 0xc000
	ds_read_b128 v[188:191], v157
	ds_read_b128 v[198:201], v157 offset:1024
	ds_read_b128 v[202:205], v157 offset:2048
	ds_read_b128 v[214:217], v157 offset:3072
	ds_read_b128 v[218:221], v157 offset:4096
	ds_read_b128 v[222:225], v157 offset:5120
	ds_read_b128 v[226:229], v157 offset:6144
	ds_read_b128 v[230:233], v157 offset:7168
	global_load_lds_dwordx4 v[192:193], off
	v_lshl_add_u64 v[192:193], s[22:23], 0, v[140:141]
	s_add_i32 m0, s30, 0xe000
	s_nop 0
	global_load_lds_dwordx4 v[192:193], off
	s_waitcnt vmcnt(8)
	s_waitcnt lgkmcnt(0)
	s_setprio 1
	s_barrier
	v_mfma_f32_16x16x32_bf16 v[124:127], v[146:149], v[188:191], v[124:127]
	v_mfma_f32_16x16x32_bf16 v[120:123], v[164:167], v[188:191], v[120:123]
	v_mfma_f32_16x16x32_bf16 v[108:111], v[146:149], v[202:205], v[108:111]
	v_mfma_f32_16x16x32_bf16 v[104:107], v[164:167], v[202:205], v[104:107]
	v_mfma_f32_16x16x32_bf16 v[92:95], v[146:149], v[218:221], v[92:95]
	v_mfma_f32_16x16x32_bf16 v[88:91], v[164:167], v[218:221], v[88:91]
	v_mfma_f32_16x16x32_bf16 v[76:79], v[146:149], v[226:229], v[76:79]
	v_mfma_f32_16x16x32_bf16 v[72:75], v[164:167], v[226:229], v[72:75]
	v_mfma_f32_16x16x32_bf16 v[124:127], v[160:163], v[198:201], v[124:127]
	v_mfma_f32_16x16x32_bf16 v[120:123], v[168:171], v[198:201], v[120:123]
	v_mfma_f32_16x16x32_bf16 v[108:111], v[160:163], v[214:217], v[108:111]
	v_mfma_f32_16x16x32_bf16 v[104:107], v[168:171], v[214:217], v[104:107]
	v_mfma_f32_16x16x32_bf16 v[92:95], v[160:163], v[222:225], v[92:95]
	v_mfma_f32_16x16x32_bf16 v[88:91], v[168:171], v[222:225], v[88:91]
	v_mfma_f32_16x16x32_bf16 v[76:79], v[160:163], v[230:233], v[76:79]
	v_mfma_f32_16x16x32_bf16 v[72:75], v[168:171], v[230:233], v[72:75]
	v_mfma_f32_16x16x32_bf16 v[116:119], v[172:175], v[188:191], v[116:119]
	v_mfma_f32_16x16x32_bf16 v[112:115], v[180:183], v[188:191], v[112:115]
	v_mfma_f32_16x16x32_bf16 v[100:103], v[172:175], v[202:205], v[100:103]
	v_mfma_f32_16x16x32_bf16 v[96:99], v[180:183], v[202:205], v[96:99]
	v_mfma_f32_16x16x32_bf16 v[84:87], v[172:175], v[218:221], v[84:87]
	v_mfma_f32_16x16x32_bf16 v[80:83], v[180:183], v[218:221], v[80:83]
	v_mfma_f32_16x16x32_bf16 v[68:71], v[172:175], v[226:229], v[68:71]
	v_mfma_f32_16x16x32_bf16 v[64:67], v[180:183], v[226:229], v[64:67]
	v_mfma_f32_16x16x32_bf16 v[116:119], v[176:179], v[198:201], v[116:119]
	v_mfma_f32_16x16x32_bf16 v[112:115], v[184:187], v[198:201], v[112:115]
	v_mfma_f32_16x16x32_bf16 v[100:103], v[176:179], v[214:217], v[100:103]
	v_mfma_f32_16x16x32_bf16 v[96:99], v[184:187], v[214:217], v[96:99]
	v_mfma_f32_16x16x32_bf16 v[84:87], v[176:179], v[222:225], v[84:87]
	v_mfma_f32_16x16x32_bf16 v[80:83], v[184:187], v[222:225], v[80:83]
	v_mfma_f32_16x16x32_bf16 v[68:71], v[176:179], v[230:233], v[68:71]
	v_mfma_f32_16x16x32_bf16 v[64:67], v[184:187], v[230:233], v[64:67]
	s_barrier
	s_setprio 0
	s_add_i32 s48, s41, s29
	v_lshl_add_u64 v[192:193], s[24:25], 0, v[130:131]
	s_mov_b32 m0, s48
	ds_read_b128 v[188:191], v157 offset:16384
	ds_read_b128 v[198:201], v157 offset:17408
	ds_read_b128 v[202:205], v157 offset:18432
	ds_read_b128 v[214:217], v157 offset:19456
	ds_read_b128 v[218:221], v157 offset:20480
	ds_read_b128 v[222:225], v157 offset:21504
	ds_read_b128 v[226:229], v157 offset:22528
	ds_read_b128 v[230:233], v157 offset:23552
	global_load_lds_dwordx4 v[192:193], off
	s_add_i32 m0, s48, 0x2000
	s_add_u32 s48, s24, 0x100000
	v_lshl_add_u64 v[206:207], s[24:25], 0, v[134:135]
	s_addc_u32 s49, s25, 0
	s_add_i32 s50, s42, s29
	global_load_lds_dwordx4 v[206:207], off
	v_lshl_add_u64 v[210:211], s[48:49], 0, v[130:131]
	s_mov_b32 m0, s50
	v_lshl_add_u64 v[234:235], s[26:27], 0, v[132:133]
	global_load_lds_dwordx4 v[210:211], off
	v_lshl_add_u64 v[210:211], s[48:49], 0, v[134:135]
	s_add_i32 m0, s50, 0x2000
	s_nop 0
	global_load_lds_dwordx4 v[210:211], off
	v_lshl_add_u64 v[210:211], s[26:27], 0, v[128:129]
	s_mov_b32 m0, s30
	s_nop 0
	global_load_lds_dwordx4 v[210:211], off
	s_mov_b32 m0, s31
	s_nop 0
	global_load_lds_dwordx4 v[234:235], off
	s_waitcnt vmcnt(8)
	s_waitcnt lgkmcnt(0)
	s_setprio 1
	s_barrier
; #define PG8_STAGE(bufoff, gbase, voff) do { _Pragma("unroll") for (int _i = 0; _i < 2; ++_i) \
;         __builtin_amdgcn_global_load_lds((const unsigned*)((const char*)(gbase) + (voff)[_i]), (LAS unsigned*)(lds + (bufoff) + ldsw + _i * 8192), 16, 0, 0); } while (0)
; #define PG8_LDA(dst, b, h) do { _Pragma("unroll") for (int m = 0; m < 4; ++m) _Pragma("unroll") for (int k = 0; k < 2; ++k) dst[m][k] = *(const LAS bf16x8*)(lds + PG8_SA(b, h) + aoff + m * 2048 + k * 1024); } while (0)
; #define PG8_LDB(dst, b, h) do { _Pragma("unroll") for (int n = 0; n < 2; ++n) _Pragma("unroll") for (int k = 0; k < 2; ++k) dst[n][k] = *(const LAS bf16x8*)(lds + PG8_SB(b, h) + boff + n * 2048 + k * 1024); } while (0)
; #define PG8_MMA(ai, bj, At, Bt) do { __builtin_amdgcn_s_setprio(1); _Pragma("unroll") for (int m = 0; m < 4; ++m) _Pragma("unroll") for (int n = 0; n < 2; ++n) _Pragma("unroll") for (int k = 0; k < 2; ++k) \
;         acc[ai][bj][m][n] = __builtin_amdgcn_mfma_f32_16x16x32_bf16(Bt[n][k], At[m][k], acc[ai][bj][m][n], 0, 0, 0); __builtin_amdgcn_s_setprio(0); } while (0)
; #define PG8_WAIT_V(n) asm volatile("s_waitcnt vmcnt(" #n ")" ::: "memory")
; #define PG8_WAIT_L(n) asm volatile("s_waitcnt lgkmcnt(" #n ")" ::: "memory")
; #define PG8_BAR __builtin_amdgcn_s_barrier()
; #define PG8_SCHED __builtin_amdgcn_sched_barrier(0)
; template <class Epi, bool ALIGN_EPI, bool SP2 = PG8_SP2_DEFAULT>
; __device__ __forceinline__ void gemm_phase(LAS unsigned char* lds, const Gemm g, const StaticOrder& S, const Epi& E) {
;     ...
;             PG8_WAIT_V(8); PG8_WAIT_L(0); PG8_BAR; PG8_MMA(1, 0, At, B0); PG8_MMA(1, 1, At, B1); PG8_BAR; PG8_SCHED;
;             PG8_LDB(B0, 1, 0); PG8_LDB(B1, 1, 1); PG8_SCHED; PG8_LDA(At, 1, 0); PG8_STAGE(PG8_SA(0, 1), a2 + hstepA, voffA);
;             PG8_WAIT_V(8); PG8_WAIT_L(0); PG8_BAR; PG8_MMA(0, 0, At, B0); PG8_MMA(0, 1, At, B1); PG8_BAR; PG8_SCHED;
	v_mfma_f32_16x16x32_bf16 v[60:63], v[146:149], v[188:191], v[60:63]
	v_mfma_f32_16x16x32_bf16 v[56:59], v[164:167], v[188:191], v[56:59]
	v_mfma_f32_16x16x32_bf16 v[44:47], v[146:149], v[202:205], v[44:47]
	v_mfma_f32_16x16x32_bf16 v[40:43], v[164:167], v[202:205], v[40:43]
	v_mfma_f32_16x16x32_bf16 v[28:31], v[146:149], v[218:221], v[28:31]
	v_mfma_f32_16x16x32_bf16 v[24:27], v[164:167], v[218:221], v[24:27]
	v_mfma_f32_16x16x32_bf16 v[12:15], v[146:149], v[226:229], v[12:15]
	v_mfma_f32_16x16x32_bf16 v[8:11], v[164:167], v[226:229], v[8:11]
	v_mfma_f32_16x16x32_bf16 v[60:63], v[160:163], v[198:201], v[60:63]
	v_mfma_f32_16x16x32_bf16 v[56:59], v[168:171], v[198:201], v[56:59]
	v_mfma_f32_16x16x32_bf16 v[44:47], v[160:163], v[214:217], v[44:47]
	v_mfma_f32_16x16x32_bf16 v[40:43], v[168:171], v[214:217], v[40:43]
	v_mfma_f32_16x16x32_bf16 v[28:31], v[160:163], v[222:225], v[28:31]
	v_mfma_f32_16x16x32_bf16 v[24:27], v[168:171], v[222:225], v[24:27]
	v_mfma_f32_16x16x32_bf16 v[12:15], v[160:163], v[230:233], v[12:15]
	v_mfma_f32_16x16x32_bf16 v[8:11], v[168:171], v[230:233], v[8:11]
	v_mfma_f32_16x16x32_bf16 v[52:55], v[172:175], v[188:191], v[52:55]
	v_mfma_f32_16x16x32_bf16 v[48:51], v[180:183], v[188:191], v[48:51]
	v_mfma_f32_16x16x32_bf16 v[36:39], v[172:175], v[202:205], v[36:39]
	v_mfma_f32_16x16x32_bf16 v[32:35], v[180:183], v[202:205], v[32:35]
	v_mfma_f32_16x16x32_bf16 v[20:23], v[172:175], v[218:221], v[20:23]
	v_mfma_f32_16x16x32_bf16 v[16:19], v[180:183], v[218:221], v[16:19]
	v_mfma_f32_16x16x32_bf16 v[4:7], v[172:175], v[226:229], v[4:7]
	v_mfma_f32_16x16x32_bf16 v[0:3], v[180:183], v[226:229], v[0:3]
	v_mfma_f32_16x16x32_bf16 v[52:55], v[176:179], v[198:201], v[52:55]
	v_mfma_f32_16x16x32_bf16 v[48:51], v[184:187], v[198:201], v[48:51]
	v_mfma_f32_16x16x32_bf16 v[36:39], v[176:179], v[214:217], v[36:39]
	v_mfma_f32_16x16x32_bf16 v[32:35], v[184:187], v[214:217], v[32:35]
	v_mfma_f32_16x16x32_bf16 v[20:23], v[176:179], v[222:225], v[20:23]
	v_mfma_f32_16x16x32_bf16 v[16:19], v[184:187], v[222:225], v[16:19]
	v_mfma_f32_16x16x32_bf16 v[4:7], v[176:179], v[230:233], v[4:7]
	v_mfma_f32_16x16x32_bf16 v[0:3], v[184:187], v[230:233], v[0:3]
	s_barrier
	s_add_i32 s48, 0, 0x18000
	v_add_u32_e32 v150, s48, v152
	s_add_i32 s49, 0, 0x1c000
	ds_read_b128 v[146:149], v150
	ds_read_b128 v[160:163], v150 offset:1024
	ds_read_b128 v[164:167], v150 offset:2048
	ds_read_b128 v[168:171], v150 offset:3072
	v_add_u32_e32 v150, s49, v152
	ds_read_b128 v[172:175], v150
	ds_read_b128 v[176:179], v150 offset:1024
	ds_read_b128 v[180:183], v150 offset:2048
	ds_read_b128 v[184:187], v150 offset:3072
	s_add_u32 s26, s26, 0x100000
	s_addc_u32 s27, s27, 0
	s_mov_b32 m0, s33
	v_lshl_add_u64 v[236:237], s[26:27], 0, v[128:129]
	ds_read_b128 v[188:191], v157 offset:32768
	ds_read_b128 v[198:201], v157 offset:33792
	ds_read_b128 v[202:205], v157 offset:34816
	ds_read_b128 v[214:217], v157 offset:35840
	ds_read_b128 v[218:221], v157 offset:36864
	ds_read_b128 v[222:225], v157 offset:37888
	ds_read_b128 v[226:229], v157 offset:38912
	ds_read_b128 v[230:233], v157 offset:39936
	global_load_lds_dwordx4 v[236:237], off
	v_lshl_add_u64 v[236:237], s[26:27], 0, v[132:133]
	s_mov_b32 m0, s34
	s_nop 0
	global_load_lds_dwordx4 v[236:237], off
	s_waitcnt vmcnt(8)
	s_waitcnt lgkmcnt(0)
	s_setprio 1
	s_barrier
	v_mfma_f32_16x16x32_bf16 v[124:127], v[146:149], v[188:191], v[124:127]
	v_mfma_f32_16x16x32_bf16 v[120:123], v[164:167], v[188:191], v[120:123]
	v_mfma_f32_16x16x32_bf16 v[108:111], v[146:149], v[202:205], v[108:111]
	v_mfma_f32_16x16x32_bf16 v[104:107], v[164:167], v[202:205], v[104:107]
	v_mfma_f32_16x16x32_bf16 v[92:95], v[146:149], v[218:221], v[92:95]
	v_mfma_f32_16x16x32_bf16 v[88:91], v[164:167], v[218:221], v[88:91]
	v_mfma_f32_16x16x32_bf16 v[76:79], v[146:149], v[226:229], v[76:79]
	v_mfma_f32_16x16x32_bf16 v[72:75], v[164:167], v[226:229], v[72:75]
	v_mfma_f32_16x16x32_bf16 v[124:127], v[160:163], v[198:201], v[124:127]
	v_mfma_f32_16x16x32_bf16 v[120:123], v[168:171], v[198:201], v[120:123]
	v_mfma_f32_16x16x32_bf16 v[108:111], v[160:163], v[214:217], v[108:111]
	v_mfma_f32_16x16x32_bf16 v[104:107], v[168:171], v[214:217], v[104:107]
	v_mfma_f32_16x16x32_bf16 v[92:95], v[160:163], v[222:225], v[92:95]
	v_mfma_f32_16x16x32_bf16 v[88:91], v[168:171], v[222:225], v[88:91]
	v_mfma_f32_16x16x32_bf16 v[76:79], v[160:163], v[230:233], v[76:79]
	v_mfma_f32_16x16x32_bf16 v[72:75], v[168:171], v[230:233], v[72:75]
	v_mfma_f32_16x16x32_bf16 v[116:119], v[172:175], v[188:191], v[116:119]
	v_mfma_f32_16x16x32_bf16 v[112:115], v[180:183], v[188:191], v[112:115]
	v_mfma_f32_16x16x32_bf16 v[100:103], v[172:175], v[202:205], v[100:103]
	v_mfma_f32_16x16x32_bf16 v[96:99], v[180:183], v[202:205], v[96:99]
	v_mfma_f32_16x16x32_bf16 v[84:87], v[172:175], v[218:221], v[84:87]
	v_mfma_f32_16x16x32_bf16 v[80:83], v[180:183], v[218:221], v[80:83]
	v_mfma_f32_16x16x32_bf16 v[68:71], v[172:175], v[226:229], v[68:71]
	v_mfma_f32_16x16x32_bf16 v[64:67], v[180:183], v[226:229], v[64:67]
	v_mfma_f32_16x16x32_bf16 v[116:119], v[176:179], v[198:201], v[116:119]
	v_mfma_f32_16x16x32_bf16 v[112:115], v[184:187], v[198:201], v[112:115]
	v_mfma_f32_16x16x32_bf16 v[100:103], v[176:179], v[214:217], v[100:103]
	v_mfma_f32_16x16x32_bf16 v[96:99], v[184:187], v[214:217], v[96:99]
	v_mfma_f32_16x16x32_bf16 v[84:87], v[176:179], v[222:225], v[84:87]
	v_mfma_f32_16x16x32_bf16 v[80:83], v[184:187], v[222:225], v[80:83]
	v_mfma_f32_16x16x32_bf16 v[68:71], v[176:179], v[230:233], v[68:71]
	v_mfma_f32_16x16x32_bf16 v[64:67], v[184:187], v[230:233], v[64:67]
	s_barrier
; #define PG8_STAGE(bufoff, gbase, voff) do { _Pragma("unroll") for (int _i = 0; _i < 2; ++_i) \
;         __builtin_amdgcn_global_load_lds((const unsigned*)((const char*)(gbase) + (voff)[_i]), (LAS unsigned*)(lds + (bufoff) + ldsw + _i * 8192), 16, 0, 0); } while (0)
; #define PG8_LDA(dst, b, h) do { _Pragma("unroll") for (int m = 0; m < 4; ++m) _Pragma("unroll") for (int k = 0; k < 2; ++k) dst[m][k] = *(const LAS bf16x8*)(lds + PG8_SA(b, h) + aoff + m * 2048 + k * 1024); } while (0)
; #define PG8_MMA(ai, bj, At, Bt) do { __builtin_amdgcn_s_setprio(1); _Pragma("unroll") for (int m = 0; m < 4; ++m) _Pragma("unroll") for (int n = 0; n < 2; ++n) _Pragma("unroll") for (int k = 0; k < 2; ++k) \
;         acc[ai][bj][m][n] = __builtin_amdgcn_mfma_f32_16x16x32_bf16(Bt[n][k], At[m][k], acc[ai][bj][m][n], 0, 0, 0); __builtin_amdgcn_s_setprio(0); } while (0)
; #define PG8_WAIT_V(n) asm volatile("s_waitcnt vmcnt(" #n ")" ::: "memory")
; #define PG8_WAIT_L(n) asm volatile("s_waitcnt lgkmcnt(" #n ")" ::: "memory")
; #define PG8_BAR __builtin_amdgcn_s_barrier()
; #define PG8_SCHED __builtin_amdgcn_sched_barrier(0)
; template <class Epi, bool ALIGN_EPI, bool SP2 = PG8_SP2_DEFAULT>
; __device__ __forceinline__ void gemm_phase(LAS unsigned char* lds, const Gemm g, const StaticOrder& S, const Epi& E) {
;     ...
;             PG8_LDA(At, 1, 1); PG8_STAGE(PG8_SB(1, 0), b3, voffB); PG8_STAGE(PG8_SB(1, 1), b3 + hstepB, voffB); PG8_STAGE(PG8_SA(1, 0), a3, voffA);
;             PG8_WAIT_V(8); PG8_WAIT_L(0); PG8_BAR; PG8_MMA(1, 0, At, B0); PG8_MMA(1, 1, At, B1); PG8_BAR; PG8_SCHED;
;     ...
;         if constexpr (ALIGN_EPI) { if (wr == 0) PG8_BAR; }
	s_setprio 0
	s_add_i32 s26, s48, s29
	v_lshl_add_u64 v[192:193], v[192:193], 0, s[12:13]
	s_mov_b32 m0, s26
	ds_read_b128 v[188:191], v157 offset:49152
	ds_read_b128 v[198:201], v157 offset:50176
	ds_read_b128 v[202:205], v157 offset:51200
	ds_read_b128 v[214:217], v157 offset:52224
	ds_read_b128 v[218:221], v157 offset:53248
	ds_read_b128 v[222:225], v157 offset:54272
	ds_read_b128 v[226:229], v157 offset:55296
	ds_read_b128 v[230:233], v157 offset:56320
	global_load_lds_dwordx4 v[192:193], off
	s_add_i32 m0, s26, 0x2000
	s_add_u32 s24, s24, 0x100080
	v_lshl_add_u64 v[192:193], v[206:207], 0, s[12:13]
	s_addc_u32 s25, s25, 0
	s_add_i32 s26, s49, s29
	global_load_lds_dwordx4 v[192:193], off
	v_lshl_add_u64 v[192:193], s[24:25], 0, v[130:131]
	s_mov_b32 m0, s26
	s_nop 0
	global_load_lds_dwordx4 v[192:193], off
	v_lshl_add_u64 v[192:193], s[24:25], 0, v[134:135]
	s_add_i32 m0, s26, 0x2000
	s_nop 0
	global_load_lds_dwordx4 v[192:193], off
	v_lshl_add_u64 v[192:193], v[210:211], 0, s[12:13]
	s_mov_b32 m0, s36
	s_nop 0
	global_load_lds_dwordx4 v[192:193], off
	v_lshl_add_u64 v[192:193], v[234:235], 0, s[12:13]
	s_mov_b32 m0, s37
	s_nop 0
	global_load_lds_dwordx4 v[192:193], off
	s_waitcnt vmcnt(8)
	s_waitcnt lgkmcnt(0)
	s_setprio 1
	s_barrier
	v_mfma_f32_16x16x32_bf16 v[60:63], v[146:149], v[188:191], v[60:63]
	v_mfma_f32_16x16x32_bf16 v[56:59], v[164:167], v[188:191], v[56:59]
	v_mfma_f32_16x16x32_bf16 v[44:47], v[146:149], v[202:205], v[44:47]
	v_mfma_f32_16x16x32_bf16 v[40:43], v[164:167], v[202:205], v[40:43]
	v_mfma_f32_16x16x32_bf16 v[28:31], v[146:149], v[218:221], v[28:31]
	v_mfma_f32_16x16x32_bf16 v[24:27], v[164:167], v[218:221], v[24:27]
	v_mfma_f32_16x16x32_bf16 v[12:15], v[146:149], v[226:229], v[12:15]
	v_mfma_f32_16x16x32_bf16 v[8:11], v[164:167], v[226:229], v[8:11]
	v_mfma_f32_16x16x32_bf16 v[60:63], v[160:163], v[198:201], v[60:63]
	v_mfma_f32_16x16x32_bf16 v[56:59], v[168:171], v[198:201], v[56:59]
	v_mfma_f32_16x16x32_bf16 v[44:47], v[160:163], v[214:217], v[44:47]
	v_mfma_f32_16x16x32_bf16 v[40:43], v[168:171], v[214:217], v[40:43]
	v_mfma_f32_16x16x32_bf16 v[28:31], v[160:163], v[222:225], v[28:31]
	v_mfma_f32_16x16x32_bf16 v[24:27], v[168:171], v[222:225], v[24:27]
	v_mfma_f32_16x16x32_bf16 v[12:15], v[160:163], v[230:233], v[12:15]
	v_mfma_f32_16x16x32_bf16 v[8:11], v[168:171], v[230:233], v[8:11]
	v_mfma_f32_16x16x32_bf16 v[52:55], v[172:175], v[188:191], v[52:55]
	v_mfma_f32_16x16x32_bf16 v[48:51], v[180:183], v[188:191], v[48:51]
	v_mfma_f32_16x16x32_bf16 v[36:39], v[172:175], v[202:205], v[36:39]
	v_mfma_f32_16x16x32_bf16 v[32:35], v[180:183], v[202:205], v[32:35]
	v_mfma_f32_16x16x32_bf16 v[20:23], v[172:175], v[218:221], v[20:23]
	v_mfma_f32_16x16x32_bf16 v[16:19], v[180:183], v[218:221], v[16:19]
	v_mfma_f32_16x16x32_bf16 v[4:7], v[172:175], v[226:229], v[4:7]
	v_mfma_f32_16x16x32_bf16 v[0:3], v[180:183], v[226:229], v[0:3]
	v_mfma_f32_16x16x32_bf16 v[52:55], v[176:179], v[198:201], v[52:55]
	v_mfma_f32_16x16x32_bf16 v[48:51], v[184:187], v[198:201], v[48:51]
	v_mfma_f32_16x16x32_bf16 v[36:39], v[176:179], v[214:217], v[36:39]
	v_mfma_f32_16x16x32_bf16 v[32:35], v[184:187], v[214:217], v[32:35]
	v_mfma_f32_16x16x32_bf16 v[20:23], v[176:179], v[222:225], v[20:23]
	v_mfma_f32_16x16x32_bf16 v[16:19], v[184:187], v[222:225], v[16:19]
	v_mfma_f32_16x16x32_bf16 v[4:7], v[176:179], v[230:233], v[4:7]
	v_mfma_f32_16x16x32_bf16 v[0:3], v[184:187], v[230:233], v[0:3]
	s_barrier
	s_add_i32 s47, s47, 2
	s_add_u32 s22, s22, 0x100
	s_addc_u32 s23, s23, 0
	s_add_u32 s44, s44, 0x100
	s_addc_u32 s45, s45, 0
	s_cmp_gt_u32 s47, 61
	s_cbranch_scc0 .LBB0_598
	s_and_b64 vcc, exec, s[14:15]
	s_cbranch_vccz .LBB0_601
	s_barrier

; #define PG8_STAGE(bufoff, gbase, voff) do { _Pragma("unroll") for (int _i = 0; _i < 2; ++_i) \
;         __builtin_amdgcn_global_load_lds((const unsigned*)((const char*)(gbase) + (voff)[_i]), (LAS unsigned*)(lds + (bufoff) + ldsw + _i * 8192), 16, 0, 0); } while (0)
; #define PG8_LDA(dst, b, h) do { _Pragma("unroll") for (int m = 0; m < 4; ++m) _Pragma("unroll") for (int k = 0; k < 2; ++k) dst[m][k] = *(const LAS bf16x8*)(lds + PG8_SA(b, h) + aoff + m * 2048 + k * 1024); } while (0)
; #define PG8_LDB(dst, b, h) do { _Pragma("unroll") for (int n = 0; n < 2; ++n) _Pragma("unroll") for (int k = 0; k < 2; ++k) dst[n][k] = *(const LAS bf16x8*)(lds + PG8_SB(b, h) + boff + n * 2048 + k * 1024); } while (0)
; #define PG8_MMA(ai, bj, At, Bt) do { __builtin_amdgcn_s_setprio(1); _Pragma("unroll") for (int m = 0; m < 4; ++m) _Pragma("unroll") for (int n = 0; n < 2; ++n) _Pragma("unroll") for (int k = 0; k < 2; ++k) \
;         acc[ai][bj][m][n] = __builtin_amdgcn_mfma_f32_16x16x32_bf16(Bt[n][k], At[m][k], acc[ai][bj][m][n], 0, 0, 0); __builtin_amdgcn_s_setprio(0); } while (0)
; #define PG8_WAIT_V(n) asm volatile("s_waitcnt vmcnt(" #n ")" ::: "memory")
; template <class Epi, bool ALIGN_EPI, bool SP2 = PG8_SP2_DEFAULT>
; __device__ __forceinline__ void gemm_phase(LAS unsigned char* lds, const Gemm g, const StaticOrder& S, const Epi& E) {
;     ...
;         const char* nA = has_next ? PG8_ABASE(nxt) : cA; const char* nB = has_next ? (const char*)g.Bt + (size_t)nxt.pn * tstepB : cB;
;         for (int t = 0; t < nt; t += 2) {
;             const bool last = (t == nt - 2);
;             const char* a1 = cA + (size_t)(t + 1) * kstep;
;             const char* a2 = last ? nA : cA + (size_t)(t + 2) * kstep; const char* b2 = last ? nB : cB + (size_t)(t + 2) * kstep;
;             const char* a3 = a2 + kstep; const char* b3 = b2 + kstep;
;             if constexpr (SP2) {
;             PG8_LDB(B0, 0, 0); PG8_LDB(B1, 0, 1); PG8_SCHED; PG8_LDA(At, 0, 0); PG8_STAGE(PG8_SA(1, 1), a1 + hstepA, voffA);
;             PG8_WAIT_V(8); PG8_WAIT_L(0); PG8_BAR; PG8_MMA(0, 0, At, B0); PG8_MMA(0, 1, At, B1); PG8_BAR; PG8_SCHED;
;             PG8_LDA(At, 0, 1); PG8_STAGE(PG8_SB(0, 0), b2, voffB); PG8_STAGE(PG8_SB(0, 1), b2 + hstepB, voffB); PG8_STAGE(PG8_SA(0, 0), a2, voffA);
;             PG8_WAIT_V(8); PG8_WAIT_L(0); PG8_BAR; PG8_MMA(1, 0, At, B0); PG8_MMA(1, 1, At, B1); PG8_BAR; PG8_SCHED;
.LBB0_804:
	ds_read_b128 v[144:147], v153
	ds_read_b128 v[156:159], v153 offset:1024
	ds_read_b128 v[160:163], v153 offset:2048
	ds_read_b128 v[164:167], v153 offset:3072
	ds_read_b128 v[168:171], v154
	ds_read_b128 v[172:175], v154 offset:1024
	ds_read_b128 v[176:179], v154 offset:2048
	ds_read_b128 v[180:183], v154 offset:3072
	s_add_u32 s22, s20, 0x100
	s_addc_u32 s23, s21, 0
	s_cmpk_eq_i32 s49, 0xa8
	s_cselect_b32 s27, s5, s23
	s_cselect_b32 s26, s4, s22
	s_cselect_b32 s25, s19, s48
	s_cselect_b32 s24, s18, s47
	v_lshl_add_u64 v[148:149], s[20:21], 0, v[136:137]
	s_add_i32 m0, s31, 0xc000
	ds_read_b128 v[184:187], v155
	ds_read_b128 v[188:191], v155 offset:1024
	ds_read_b128 v[192:195], v155 offset:2048
	ds_read_b128 v[196:199], v155 offset:3072
	ds_read_b128 v[200:203], v155 offset:4096
	ds_read_b128 v[204:207], v155 offset:5120
	ds_read_b128 v[208:211], v155 offset:6144
	ds_read_b128 v[212:215], v155 offset:7168
	global_load_lds_dwordx4 v[148:149], off
	v_lshl_add_u64 v[148:149], s[20:21], 0, v[138:139]
	s_add_i32 m0, s31, 0xe000
	s_nop 0
	global_load_lds_dwordx4 v[148:149], off
	s_waitcnt vmcnt(8)
	s_waitcnt lgkmcnt(0)
	s_setprio 1
	s_barrier
	v_mfma_f32_16x16x32_bf16 v[124:127], v[144:147], v[184:187], v[124:127]
	v_mfma_f32_16x16x32_bf16 v[120:123], v[160:163], v[184:187], v[120:123]
	v_mfma_f32_16x16x32_bf16 v[108:111], v[144:147], v[192:195], v[108:111]
	v_mfma_f32_16x16x32_bf16 v[104:107], v[160:163], v[192:195], v[104:107]
	v_mfma_f32_16x16x32_bf16 v[92:95], v[144:147], v[200:203], v[92:95]
	v_mfma_f32_16x16x32_bf16 v[88:91], v[160:163], v[200:203], v[88:91]
	v_mfma_f32_16x16x32_bf16 v[76:79], v[144:147], v[208:211], v[76:79]
	v_mfma_f32_16x16x32_bf16 v[72:75], v[160:163], v[208:211], v[72:75]
	v_mfma_f32_16x16x32_bf16 v[124:127], v[156:159], v[188:191], v[124:127]
	v_mfma_f32_16x16x32_bf16 v[120:123], v[164:167], v[188:191], v[120:123]
	v_mfma_f32_16x16x32_bf16 v[108:111], v[156:159], v[196:199], v[108:111]
	v_mfma_f32_16x16x32_bf16 v[104:107], v[164:167], v[196:199], v[104:107]
	v_mfma_f32_16x16x32_bf16 v[92:95], v[156:159], v[204:207], v[92:95]
	v_mfma_f32_16x16x32_bf16 v[88:91], v[164:167], v[204:207], v[88:91]
	v_mfma_f32_16x16x32_bf16 v[76:79], v[156:159], v[212:215], v[76:79]
	v_mfma_f32_16x16x32_bf16 v[72:75], v[164:167], v[212:215], v[72:75]
	v_mfma_f32_16x16x32_bf16 v[116:119], v[168:171], v[184:187], v[116:119]
	v_mfma_f32_16x16x32_bf16 v[112:115], v[176:179], v[184:187], v[112:115]
	v_mfma_f32_16x16x32_bf16 v[100:103], v[168:171], v[192:195], v[100:103]
	v_mfma_f32_16x16x32_bf16 v[96:99], v[176:179], v[192:195], v[96:99]
	v_mfma_f32_16x16x32_bf16 v[84:87], v[168:171], v[200:203], v[84:87]
	v_mfma_f32_16x16x32_bf16 v[80:83], v[176:179], v[200:203], v[80:83]
	v_mfma_f32_16x16x32_bf16 v[68:71], v[168:171], v[208:211], v[68:71]
	v_mfma_f32_16x16x32_bf16 v[64:67], v[176:179], v[208:211], v[64:67]
	v_mfma_f32_16x16x32_bf16 v[116:119], v[172:175], v[188:191], v[116:119]
	v_mfma_f32_16x16x32_bf16 v[112:115], v[180:183], v[188:191], v[112:115]
	v_mfma_f32_16x16x32_bf16 v[100:103], v[172:175], v[196:199], v[100:103]
	v_mfma_f32_16x16x32_bf16 v[96:99], v[180:183], v[196:199], v[96:99]
	v_mfma_f32_16x16x32_bf16 v[84:87], v[172:175], v[204:207], v[84:87]
	v_mfma_f32_16x16x32_bf16 v[80:83], v[180:183], v[204:207], v[80:83]
	v_mfma_f32_16x16x32_bf16 v[68:71], v[172:175], v[212:215], v[68:71]
	v_mfma_f32_16x16x32_bf16 v[64:67], v[180:183], v[212:215], v[64:67]
	s_barrier
	s_setprio 0
	s_add_i32 s20, s40, s28
	v_lshl_add_u64 v[148:149], s[24:25], 0, v[130:131]
	s_mov_b32 m0, s20
	ds_read_b128 v[184:187], v155 offset:16384
	ds_read_b128 v[188:191], v155 offset:17408
	ds_read_b128 v[192:195], v155 offset:18432
	ds_read_b128 v[196:199], v155 offset:19456
	ds_read_b128 v[200:203], v155 offset:20480
	ds_read_b128 v[204:207], v155 offset:21504
	ds_read_b128 v[208:211], v155 offset:22528
	ds_read_b128 v[212:215], v155 offset:23552
	global_load_lds_dwordx4 v[148:149], off
	s_add_i32 m0, s20, 0x2000
	s_add_u32 s20, s24, 0x2b0000
	v_lshl_add_u64 v[216:217], s[24:25], 0, v[134:135]
	s_addc_u32 s21, s25, 0
	s_add_i32 s50, s41, s28
	global_load_lds_dwordx4 v[216:217], off
	v_lshl_add_u64 v[218:219], s[20:21], 0, v[130:131]
	s_mov_b32 m0, s50
	v_lshl_add_u64 v[220:221], s[26:27], 0, v[132:133]
	global_load_lds_dwordx4 v[218:219], off
	v_lshl_add_u64 v[218:219], s[20:21], 0, v[134:135]
	s_add_i32 m0, s50, 0x2000
	s_nop 0
	global_load_lds_dwordx4 v[218:219], off
	v_lshl_add_u64 v[218:219], s[26:27], 0, v[128:129]
	s_mov_b32 m0, s31
	s_nop 0
	global_load_lds_dwordx4 v[218:219], off
	s_mov_b32 m0, s33
	s_nop 0
	global_load_lds_dwordx4 v[220:221], off
	s_waitcnt vmcnt(8)
	s_waitcnt lgkmcnt(0)
	s_setprio 1
	s_barrier
; #define PG8_STAGE(bufoff, gbase, voff) do { _Pragma("unroll") for (int _i = 0; _i < 2; ++_i) \
;         __builtin_amdgcn_global_load_lds((const unsigned*)((const char*)(gbase) + (voff)[_i]), (LAS unsigned*)(lds + (bufoff) + ldsw + _i * 8192), 16, 0, 0); } while (0)
; #define PG8_LDA(dst, b, h) do { _Pragma("unroll") for (int m = 0; m < 4; ++m) _Pragma("unroll") for (int k = 0; k < 2; ++k) dst[m][k] = *(const LAS bf16x8*)(lds + PG8_SA(b, h) + aoff + m * 2048 + k * 1024); } while (0)
; #define PG8_LDB(dst, b, h) do { _Pragma("unroll") for (int n = 0; n < 2; ++n) _Pragma("unroll") for (int k = 0; k < 2; ++k) dst[n][k] = *(const LAS bf16x8*)(lds + PG8_SB(b, h) + boff + n * 2048 + k * 1024); } while (0)
; #define PG8_MMA(ai, bj, At, Bt) do { __builtin_amdgcn_s_setprio(1); _Pragma("unroll") for (int m = 0; m < 4; ++m) _Pragma("unroll") for (int n = 0; n < 2; ++n) _Pragma("unroll") for (int k = 0; k < 2; ++k) \
;         acc[ai][bj][m][n] = __builtin_amdgcn_mfma_f32_16x16x32_bf16(Bt[n][k], At[m][k], acc[ai][bj][m][n], 0, 0, 0); __builtin_amdgcn_s_setprio(0); } while (0)
; #define PG8_WAIT_V(n) asm volatile("s_waitcnt vmcnt(" #n ")" ::: "memory")
; #define PG8_WAIT_L(n) asm volatile("s_waitcnt lgkmcnt(" #n ")" ::: "memory")
; #define PG8_BAR __builtin_amdgcn_s_barrier()
; #define PG8_SCHED __builtin_amdgcn_sched_barrier(0)
; template <class Epi, bool ALIGN_EPI, bool SP2 = PG8_SP2_DEFAULT>
; __device__ __forceinline__ void gemm_phase(LAS unsigned char* lds, const Gemm g, const StaticOrder& S, const Epi& E) {
;     ...
;             PG8_WAIT_V(8); PG8_WAIT_L(0); PG8_BAR; PG8_MMA(1, 0, At, B0); PG8_MMA(1, 1, At, B1); PG8_BAR; PG8_SCHED;
;             PG8_LDB(B0, 1, 0); PG8_LDB(B1, 1, 1); PG8_SCHED; PG8_LDA(At, 1, 0); PG8_STAGE(PG8_SA(0, 1), a2 + hstepA, voffA);
;             PG8_WAIT_V(8); PG8_WAIT_L(0); PG8_BAR; PG8_MMA(0, 0, At, B0); PG8_MMA(0, 1, At, B1); PG8_BAR; PG8_SCHED;
	v_mfma_f32_16x16x32_bf16 v[60:63], v[144:147], v[184:187], v[60:63]
	v_mfma_f32_16x16x32_bf16 v[56:59], v[160:163], v[184:187], v[56:59]
	v_mfma_f32_16x16x32_bf16 v[44:47], v[144:147], v[192:195], v[44:47]
	v_mfma_f32_16x16x32_bf16 v[40:43], v[160:163], v[192:195], v[40:43]
	v_mfma_f32_16x16x32_bf16 v[28:31], v[144:147], v[200:203], v[28:31]
	v_mfma_f32_16x16x32_bf16 v[24:27], v[160:163], v[200:203], v[24:27]
	v_mfma_f32_16x16x32_bf16 v[12:15], v[144:147], v[208:211], v[12:15]
	v_mfma_f32_16x16x32_bf16 v[8:11], v[160:163], v[208:211], v[8:11]
	v_mfma_f32_16x16x32_bf16 v[60:63], v[156:159], v[188:191], v[60:63]
	v_mfma_f32_16x16x32_bf16 v[56:59], v[164:167], v[188:191], v[56:59]
	v_mfma_f32_16x16x32_bf16 v[44:47], v[156:159], v[196:199], v[44:47]
	v_mfma_f32_16x16x32_bf16 v[40:43], v[164:167], v[196:199], v[40:43]
	v_mfma_f32_16x16x32_bf16 v[28:31], v[156:159], v[204:207], v[28:31]
	v_mfma_f32_16x16x32_bf16 v[24:27], v[164:167], v[204:207], v[24:27]
	v_mfma_f32_16x16x32_bf16 v[12:15], v[156:159], v[212:215], v[12:15]
	v_mfma_f32_16x16x32_bf16 v[8:11], v[164:167], v[212:215], v[8:11]
	v_mfma_f32_16x16x32_bf16 v[52:55], v[168:171], v[184:187], v[52:55]
	v_mfma_f32_16x16x32_bf16 v[48:51], v[176:179], v[184:187], v[48:51]
	v_mfma_f32_16x16x32_bf16 v[36:39], v[168:171], v[192:195], v[36:39]
	v_mfma_f32_16x16x32_bf16 v[32:35], v[176:179], v[192:195], v[32:35]
	v_mfma_f32_16x16x32_bf16 v[20:23], v[168:171], v[200:203], v[20:23]
	v_mfma_f32_16x16x32_bf16 v[16:19], v[176:179], v[200:203], v[16:19]
	v_mfma_f32_16x16x32_bf16 v[4:7], v[168:171], v[208:211], v[4:7]
	v_mfma_f32_16x16x32_bf16 v[0:3], v[176:179], v[208:211], v[0:3]
	v_mfma_f32_16x16x32_bf16 v[52:55], v[172:175], v[188:191], v[52:55]
	v_mfma_f32_16x16x32_bf16 v[48:51], v[180:183], v[188:191], v[48:51]
	v_mfma_f32_16x16x32_bf16 v[36:39], v[172:175], v[196:199], v[36:39]
	v_mfma_f32_16x16x32_bf16 v[32:35], v[180:183], v[196:199], v[32:35]
	v_mfma_f32_16x16x32_bf16 v[20:23], v[172:175], v[204:207], v[20:23]
	v_mfma_f32_16x16x32_bf16 v[16:19], v[180:183], v[204:207], v[16:19]
	v_mfma_f32_16x16x32_bf16 v[4:7], v[172:175], v[212:215], v[4:7]
	v_mfma_f32_16x16x32_bf16 v[0:3], v[180:183], v[212:215], v[0:3]
	s_barrier
	s_add_i32 s50, 0, 0x18000
	s_add_i32 s51, 0, 0x1c000
	v_add_u32_e32 v164, s50, v151
	v_add_u32_e32 v180, s51, v151
	ds_read_b128 v[144:147], v164
	ds_read_b128 v[156:159], v164 offset:1024
	ds_read_b128 v[160:163], v164 offset:2048
	ds_read_b128 v[164:167], v164 offset:3072
	ds_read_b128 v[168:171], v180
	ds_read_b128 v[172:175], v180 offset:1024
	ds_read_b128 v[176:179], v180 offset:2048
	ds_read_b128 v[180:183], v180 offset:3072
	s_add_u32 s20, s26, 0x2b0000
	s_addc_u32 s21, s27, 0
	s_mov_b32 m0, s34
	v_lshl_add_u64 v[222:223], s[20:21], 0, v[128:129]
	ds_read_b128 v[184:187], v155 offset:32768
	ds_read_b128 v[188:191], v155 offset:33792
	ds_read_b128 v[192:195], v155 offset:34816
	ds_read_b128 v[196:199], v155 offset:35840
	ds_read_b128 v[200:203], v155 offset:36864
	ds_read_b128 v[204:207], v155 offset:37888
	ds_read_b128 v[208:211], v155 offset:38912
	ds_read_b128 v[212:215], v155 offset:39936
	global_load_lds_dwordx4 v[222:223], off
	v_lshl_add_u64 v[222:223], s[20:21], 0, v[132:133]
	s_mov_b32 m0, s35
	s_nop 0
	global_load_lds_dwordx4 v[222:223], off
	s_waitcnt vmcnt(8)
	s_waitcnt lgkmcnt(0)
	s_setprio 1
	s_barrier
	v_mfma_f32_16x16x32_bf16 v[124:127], v[144:147], v[184:187], v[124:127]
	v_mfma_f32_16x16x32_bf16 v[120:123], v[160:163], v[184:187], v[120:123]
	v_mfma_f32_16x16x32_bf16 v[108:111], v[144:147], v[192:195], v[108:111]
	v_mfma_f32_16x16x32_bf16 v[104:107], v[160:163], v[192:195], v[104:107]
	v_mfma_f32_16x16x32_bf16 v[92:95], v[144:147], v[200:203], v[92:95]
	v_mfma_f32_16x16x32_bf16 v[88:91], v[160:163], v[200:203], v[88:91]
	v_mfma_f32_16x16x32_bf16 v[76:79], v[144:147], v[208:211], v[76:79]
	v_mfma_f32_16x16x32_bf16 v[72:75], v[160:163], v[208:211], v[72:75]
	v_mfma_f32_16x16x32_bf16 v[124:127], v[156:159], v[188:191], v[124:127]
	v_mfma_f32_16x16x32_bf16 v[120:123], v[164:167], v[188:191], v[120:123]
	v_mfma_f32_16x16x32_bf16 v[108:111], v[156:159], v[196:199], v[108:111]
	v_mfma_f32_16x16x32_bf16 v[104:107], v[164:167], v[196:199], v[104:107]
	v_mfma_f32_16x16x32_bf16 v[92:95], v[156:159], v[204:207], v[92:95]
	v_mfma_f32_16x16x32_bf16 v[88:91], v[164:167], v[204:207], v[88:91]
	v_mfma_f32_16x16x32_bf16 v[76:79], v[156:159], v[212:215], v[76:79]
	v_mfma_f32_16x16x32_bf16 v[72:75], v[164:167], v[212:215], v[72:75]
	v_mfma_f32_16x16x32_bf16 v[116:119], v[168:171], v[184:187], v[116:119]
	v_mfma_f32_16x16x32_bf16 v[112:115], v[176:179], v[184:187], v[112:115]
	v_mfma_f32_16x16x32_bf16 v[100:103], v[168:171], v[192:195], v[100:103]
	v_mfma_f32_16x16x32_bf16 v[96:99], v[176:179], v[192:195], v[96:99]
	v_mfma_f32_16x16x32_bf16 v[84:87], v[168:171], v[200:203], v[84:87]
	v_mfma_f32_16x16x32_bf16 v[80:83], v[176:179], v[200:203], v[80:83]
	v_mfma_f32_16x16x32_bf16 v[68:71], v[168:171], v[208:211], v[68:71]
	v_mfma_f32_16x16x32_bf16 v[64:67], v[176:179], v[208:211], v[64:67]
	v_mfma_f32_16x16x32_bf16 v[116:119], v[172:175], v[188:191], v[116:119]
	v_mfma_f32_16x16x32_bf16 v[112:115], v[180:183], v[188:191], v[112:115]
	v_mfma_f32_16x16x32_bf16 v[100:103], v[172:175], v[196:199], v[100:103]
	v_mfma_f32_16x16x32_bf16 v[96:99], v[180:183], v[196:199], v[96:99]
	v_mfma_f32_16x16x32_bf16 v[84:87], v[172:175], v[204:207], v[84:87]
	v_mfma_f32_16x16x32_bf16 v[80:83], v[180:183], v[204:207], v[80:83]
	v_mfma_f32_16x16x32_bf16 v[68:71], v[172:175], v[212:215], v[68:71]
	v_mfma_f32_16x16x32_bf16 v[64:67], v[180:183], v[212:215], v[64:67]
	s_barrier
; #define PG8_STAGE(bufoff, gbase, voff) do { _Pragma("unroll") for (int _i = 0; _i < 2; ++_i) \
;         __builtin_amdgcn_global_load_lds((const unsigned*)((const char*)(gbase) + (voff)[_i]), (LAS unsigned*)(lds + (bufoff) + ldsw + _i * 8192), 16, 0, 0); } while (0)
; #define PG8_LDA(dst, b, h) do { _Pragma("unroll") for (int m = 0; m < 4; ++m) _Pragma("unroll") for (int k = 0; k < 2; ++k) dst[m][k] = *(const LAS bf16x8*)(lds + PG8_SA(b, h) + aoff + m * 2048 + k * 1024); } while (0)
; #define PG8_MMA(ai, bj, At, Bt) do { __builtin_amdgcn_s_setprio(1); _Pragma("unroll") for (int m = 0; m < 4; ++m) _Pragma("unroll") for (int n = 0; n < 2; ++n) _Pragma("unroll") for (int k = 0; k < 2; ++k) \
;         acc[ai][bj][m][n] = __builtin_amdgcn_mfma_f32_16x16x32_bf16(Bt[n][k], At[m][k], acc[ai][bj][m][n], 0, 0, 0); __builtin_amdgcn_s_setprio(0); } while (0)
; #define PG8_WAIT_V(n) asm volatile("s_waitcnt vmcnt(" #n ")" ::: "memory")
; #define PG8_WAIT_L(n) asm volatile("s_waitcnt lgkmcnt(" #n ")" ::: "memory")
; #define PG8_BAR __builtin_amdgcn_s_barrier()
; #define PG8_SCHED __builtin_amdgcn_sched_barrier(0)
; template <class Epi, bool ALIGN_EPI, bool SP2 = PG8_SP2_DEFAULT>
; __device__ __forceinline__ void gemm_phase(LAS unsigned char* lds, const Gemm g, const StaticOrder& S, const Epi& E) {
;     ...
;             PG8_LDA(At, 1, 1); PG8_STAGE(PG8_SB(1, 0), b3, voffB); PG8_STAGE(PG8_SB(1, 1), b3 + hstepB, voffB); PG8_STAGE(PG8_SA(1, 0), a3, voffA);
;             PG8_WAIT_V(8); PG8_WAIT_L(0); PG8_BAR; PG8_MMA(1, 0, At, B0); PG8_MMA(1, 1, At, B1); PG8_BAR; PG8_SCHED;
;     ...
;         if constexpr (ALIGN_EPI) { if (wr == 0) PG8_BAR; }
	s_setprio 0
	s_add_i32 s20, s50, s28
	v_lshl_add_u64 v[148:149], v[148:149], 0, s[6:7]
	s_mov_b32 m0, s20
	ds_read_b128 v[184:187], v155 offset:49152
	ds_read_b128 v[188:191], v155 offset:50176
	ds_read_b128 v[192:195], v155 offset:51200
	ds_read_b128 v[196:199], v155 offset:52224
	ds_read_b128 v[200:203], v155 offset:53248
	ds_read_b128 v[204:207], v155 offset:54272
	ds_read_b128 v[208:211], v155 offset:55296
	ds_read_b128 v[212:215], v155 offset:56320
	global_load_lds_dwordx4 v[148:149], off
	s_add_i32 m0, s20, 0x2000
	s_add_u32 s20, s24, 0x2b0080
	v_lshl_add_u64 v[148:149], v[216:217], 0, s[6:7]
	s_addc_u32 s21, s25, 0
	s_add_i32 s24, s51, s28
	global_load_lds_dwordx4 v[148:149], off
	v_lshl_add_u64 v[148:149], s[20:21], 0, v[130:131]
	s_mov_b32 m0, s24
	s_nop 0
	global_load_lds_dwordx4 v[148:149], off
	v_lshl_add_u64 v[148:149], s[20:21], 0, v[134:135]
	s_add_i32 m0, s24, 0x2000
	s_nop 0
	global_load_lds_dwordx4 v[148:149], off
	v_lshl_add_u64 v[148:149], v[218:219], 0, s[6:7]
	s_mov_b32 m0, s37
	s_nop 0
	global_load_lds_dwordx4 v[148:149], off
	v_lshl_add_u64 v[148:149], v[220:221], 0, s[6:7]
	s_mov_b32 m0, s38
	s_nop 0
	global_load_lds_dwordx4 v[148:149], off
	s_waitcnt vmcnt(8)
	s_waitcnt lgkmcnt(0)
	s_setprio 1
	s_barrier
	v_mfma_f32_16x16x32_bf16 v[60:63], v[144:147], v[184:187], v[60:63]
	v_mfma_f32_16x16x32_bf16 v[56:59], v[160:163], v[184:187], v[56:59]
	v_mfma_f32_16x16x32_bf16 v[44:47], v[144:147], v[192:195], v[44:47]
	v_mfma_f32_16x16x32_bf16 v[40:43], v[160:163], v[192:195], v[40:43]
	v_mfma_f32_16x16x32_bf16 v[28:31], v[144:147], v[200:203], v[28:31]
	v_mfma_f32_16x16x32_bf16 v[24:27], v[160:163], v[200:203], v[24:27]
	v_mfma_f32_16x16x32_bf16 v[12:15], v[144:147], v[208:211], v[12:15]
	v_mfma_f32_16x16x32_bf16 v[8:11], v[160:163], v[208:211], v[8:11]
	v_mfma_f32_16x16x32_bf16 v[60:63], v[156:159], v[188:191], v[60:63]
	v_mfma_f32_16x16x32_bf16 v[56:59], v[164:167], v[188:191], v[56:59]
	v_mfma_f32_16x16x32_bf16 v[44:47], v[156:159], v[196:199], v[44:47]
	v_mfma_f32_16x16x32_bf16 v[40:43], v[164:167], v[196:199], v[40:43]
	v_mfma_f32_16x16x32_bf16 v[28:31], v[156:159], v[204:207], v[28:31]
	v_mfma_f32_16x16x32_bf16 v[24:27], v[164:167], v[204:207], v[24:27]
	v_mfma_f32_16x16x32_bf16 v[12:15], v[156:159], v[212:215], v[12:15]
	v_mfma_f32_16x16x32_bf16 v[8:11], v[164:167], v[212:215], v[8:11]
	v_mfma_f32_16x16x32_bf16 v[52:55], v[168:171], v[184:187], v[52:55]
	v_mfma_f32_16x16x32_bf16 v[48:51], v[176:179], v[184:187], v[48:51]
	v_mfma_f32_16x16x32_bf16 v[36:39], v[168:171], v[192:195], v[36:39]
	v_mfma_f32_16x16x32_bf16 v[32:35], v[176:179], v[192:195], v[32:35]
	v_mfma_f32_16x16x32_bf16 v[20:23], v[168:171], v[200:203], v[20:23]
	v_mfma_f32_16x16x32_bf16 v[16:19], v[176:179], v[200:203], v[16:19]
	v_mfma_f32_16x16x32_bf16 v[4:7], v[168:171], v[208:211], v[4:7]
	v_mfma_f32_16x16x32_bf16 v[0:3], v[176:179], v[208:211], v[0:3]
	v_mfma_f32_16x16x32_bf16 v[52:55], v[172:175], v[188:191], v[52:55]
	v_mfma_f32_16x16x32_bf16 v[48:51], v[180:183], v[188:191], v[48:51]
	v_mfma_f32_16x16x32_bf16 v[36:39], v[172:175], v[196:199], v[36:39]
	v_mfma_f32_16x16x32_bf16 v[32:35], v[180:183], v[196:199], v[32:35]
	v_mfma_f32_16x16x32_bf16 v[20:23], v[172:175], v[204:207], v[20:23]
	v_mfma_f32_16x16x32_bf16 v[16:19], v[180:183], v[204:207], v[16:19]
	v_mfma_f32_16x16x32_bf16 v[4:7], v[172:175], v[212:215], v[4:7]
	v_mfma_f32_16x16x32_bf16 v[0:3], v[180:183], v[212:215], v[0:3]
	s_barrier
	s_add_i32 s49, s49, 2
	s_add_u32 s47, s47, 0x100
	s_addc_u32 s48, s48, 0
	s_cmpk_gt_u32 s49, 0xa9
	s_mov_b64 s[20:21], s[22:23]
	s_cbranch_scc0 .LBB0_804
	s_and_b64 vcc, exec, s[8:9]
	s_cbranch_vccz .LBB0_807
	s_barrier
